# v42 + merged vmcnt/lgkmcnt waits before GEMM load-segment barriers
# speedup vs baseline: 1.0096x; 1.0025x over previous
.LBB0_194:
	s_add_u32 s24, s22, 0xfffc0080
	s_addc_u32 s25, s23, -1
	s_add_i32 s55, 0, 0x10000
	s_cmp_eq_u32 s54, 12
	s_cselect_b32 s27, s15, s25
	s_cselect_b32 s26, s46, s24
	v_add_u32_e32 v140, s55, v143
	s_cselect_b32 s25, s13, s53
	s_cselect_b32 s24, s47, s52
	s_add_i32 s69, 0, 0x14000
	ds_read_b128 v[162:165], v140
	ds_read_b128 v[166:169], v140 offset:1024
	ds_read_b128 v[170:173], v140 offset:2048
	ds_read_b128 v[174:177], v140 offset:3072
	v_add_u32_e32 v140, s69, v143
	ds_read_b128 v[178:181], v140
	ds_read_b128 v[182:185], v140 offset:1024
	ds_read_b128 v[186:189], v140 offset:2048
	ds_read_b128 v[190:193], v140 offset:3072
	v_lshl_add_u64 v[140:141], s[22:23], 0, v[136:137]
	s_add_i32 m0, s38, 0xc000
	ds_read_b128 v[194:197], v145
	ds_read_b128 v[198:201], v145 offset:1024
	ds_read_b128 v[202:205], v145 offset:2048
	ds_read_b128 v[206:209], v145 offset:3072
	ds_read_b128 v[232:235], v145 offset:4096
	ds_read_b128 v[236:239], v145 offset:5120
	ds_read_b128 v[240:243], v145 offset:6144
	ds_read_b128 v[244:247], v145 offset:7168
	global_load_lds_dwordx4 v[140:141], off
	v_lshl_add_u64 v[140:141], s[22:23], 0, v[138:139]
	s_add_i32 m0, s38, 0xe000
	s_nop 0
	global_load_lds_dwordx4 v[140:141], off
	s_waitcnt vmcnt(8) lgkmcnt(0)
	s_barrier
	s_setprio 1
	v_mfma_f32_16x16x32_bf16 v[126:129], v[162:165], v[194:197], v[126:129]
	v_mfma_f32_16x16x32_bf16 v[118:121], v[170:173], v[194:197], v[118:121]
	v_mfma_f32_16x16x32_bf16 v[110:113], v[162:165], v[202:205], v[110:113]
	v_mfma_f32_16x16x32_bf16 v[102:105], v[170:173], v[202:205], v[102:105]
	v_mfma_f32_16x16x32_bf16 v[94:97], v[162:165], v[232:235], v[94:97]
	v_mfma_f32_16x16x32_bf16 v[86:89], v[170:173], v[232:235], v[86:89]
	v_mfma_f32_16x16x32_bf16 v[78:81], v[162:165], v[240:243], v[78:81]
	v_mfma_f32_16x16x32_bf16 v[70:73], v[170:173], v[240:243], v[70:73]
	v_mfma_f32_16x16x32_bf16 v[126:129], v[166:169], v[198:201], v[126:129]
	v_mfma_f32_16x16x32_bf16 v[118:121], v[174:177], v[198:201], v[118:121]
	v_mfma_f32_16x16x32_bf16 v[110:113], v[166:169], v[206:209], v[110:113]
	v_mfma_f32_16x16x32_bf16 v[102:105], v[174:177], v[206:209], v[102:105]
	v_mfma_f32_16x16x32_bf16 v[94:97], v[166:169], v[236:239], v[94:97]
	v_mfma_f32_16x16x32_bf16 v[86:89], v[174:177], v[236:239], v[86:89]
	v_mfma_f32_16x16x32_bf16 v[78:81], v[166:169], v[244:247], v[78:81]
	v_mfma_f32_16x16x32_bf16 v[70:73], v[174:177], v[244:247], v[70:73]
	v_mfma_f32_16x16x32_bf16 v[122:125], v[178:181], v[194:197], v[122:125]
	v_mfma_f32_16x16x32_bf16 v[114:117], v[186:189], v[194:197], v[114:117]
	v_mfma_f32_16x16x32_bf16 v[106:109], v[178:181], v[202:205], v[106:109]
	v_mfma_f32_16x16x32_bf16 v[98:101], v[186:189], v[202:205], v[98:101]
	v_mfma_f32_16x16x32_bf16 v[90:93], v[178:181], v[232:235], v[90:93]
	v_mfma_f32_16x16x32_bf16 v[82:85], v[186:189], v[232:235], v[82:85]
	v_mfma_f32_16x16x32_bf16 v[74:77], v[178:181], v[240:243], v[74:77]
	v_mfma_f32_16x16x32_bf16 v[66:69], v[186:189], v[240:243], v[66:69]
	v_mfma_f32_16x16x32_bf16 v[122:125], v[182:185], v[198:201], v[122:125]
	v_mfma_f32_16x16x32_bf16 v[114:117], v[190:193], v[198:201], v[114:117]
	v_mfma_f32_16x16x32_bf16 v[106:109], v[182:185], v[206:209], v[106:109]
	v_mfma_f32_16x16x32_bf16 v[98:101], v[190:193], v[206:209], v[98:101]
	v_mfma_f32_16x16x32_bf16 v[90:93], v[182:185], v[236:239], v[90:93]
	v_mfma_f32_16x16x32_bf16 v[82:85], v[190:193], v[236:239], v[82:85]
	v_mfma_f32_16x16x32_bf16 v[74:77], v[182:185], v[244:247], v[74:77]
	v_mfma_f32_16x16x32_bf16 v[66:69], v[190:193], v[244:247], v[66:69]
	s_setprio 0
	s_barrier
	s_add_i32 s55, s55, s36
	v_lshl_add_u64 v[140:141], s[24:25], 0, v[0:1]
	s_mov_b32 m0, s55
	ds_read_b128 v[194:197], v145 offset:16384
	ds_read_b128 v[198:201], v145 offset:17408
	ds_read_b128 v[202:205], v145 offset:18432
	ds_read_b128 v[206:209], v145 offset:19456
	ds_read_b128 v[232:235], v145 offset:20480
	ds_read_b128 v[236:239], v145 offset:21504
	ds_read_b128 v[240:243], v145 offset:22528
	ds_read_b128 v[244:247], v145 offset:23552
	global_load_lds_dwordx4 v[140:141], off
	s_add_i32 m0, s55, 0x2000
	s_add_u32 s56, s24, 0x40000
	v_lshl_add_u64 v[210:211], s[24:25], 0, v[130:131]
	s_addc_u32 s57, s25, 0
	s_add_i32 s55, s69, s36
	global_load_lds_dwordx4 v[210:211], off
	v_lshl_add_u64 v[220:221], s[56:57], 0, v[0:1]
	s_mov_b32 m0, s55
	v_lshl_add_u64 v[222:223], s[26:27], 0, v[132:133]
	global_load_lds_dwordx4 v[220:221], off
	v_lshl_add_u64 v[220:221], s[56:57], 0, v[130:131]
	s_add_i32 m0, s55, 0x2000
	s_nop 0
	global_load_lds_dwordx4 v[220:221], off
	v_lshl_add_u64 v[220:221], s[26:27], 0, v[134:135]
	s_mov_b32 m0, s38
	s_nop 0
	global_load_lds_dwordx4 v[220:221], off
	s_mov_b32 m0, s39
	s_nop 0
	global_load_lds_dwordx4 v[222:223], off
	s_waitcnt vmcnt(8) lgkmcnt(0)
	s_barrier
	s_setprio 1
	v_mfma_f32_16x16x32_bf16 v[62:65], v[162:165], v[194:197], v[62:65]
	v_mfma_f32_16x16x32_bf16 v[54:57], v[170:173], v[194:197], v[54:57]
	v_mfma_f32_16x16x32_bf16 v[46:49], v[162:165], v[202:205], v[46:49]
	v_mfma_f32_16x16x32_bf16 v[38:41], v[170:173], v[202:205], v[38:41]
	v_mfma_f32_16x16x32_bf16 v[30:33], v[162:165], v[232:235], v[30:33]
	v_mfma_f32_16x16x32_bf16 v[22:25], v[170:173], v[232:235], v[22:25]
	v_mfma_f32_16x16x32_bf16 v[14:17], v[162:165], v[240:243], v[14:17]
	v_mfma_f32_16x16x32_bf16 v[6:9], v[170:173], v[240:243], v[6:9]
	v_mfma_f32_16x16x32_bf16 v[62:65], v[166:169], v[198:201], v[62:65]
	v_mfma_f32_16x16x32_bf16 v[54:57], v[174:177], v[198:201], v[54:57]
	v_mfma_f32_16x16x32_bf16 v[46:49], v[166:169], v[206:209], v[46:49]
	v_mfma_f32_16x16x32_bf16 v[38:41], v[174:177], v[206:209], v[38:41]
	v_mfma_f32_16x16x32_bf16 v[30:33], v[166:169], v[236:239], v[30:33]
	v_mfma_f32_16x16x32_bf16 v[22:25], v[174:177], v[236:239], v[22:25]
	v_mfma_f32_16x16x32_bf16 v[14:17], v[166:169], v[244:247], v[14:17]
	v_mfma_f32_16x16x32_bf16 v[6:9], v[174:177], v[244:247], v[6:9]
	v_mfma_f32_16x16x32_bf16 v[58:61], v[178:181], v[194:197], v[58:61]
	v_mfma_f32_16x16x32_bf16 v[50:53], v[186:189], v[194:197], v[50:53]
	v_mfma_f32_16x16x32_bf16 v[42:45], v[178:181], v[202:205], v[42:45]
	v_mfma_f32_16x16x32_bf16 v[34:37], v[186:189], v[202:205], v[34:37]
	v_mfma_f32_16x16x32_bf16 v[26:29], v[178:181], v[232:235], v[26:29]
	v_mfma_f32_16x16x32_bf16 v[18:21], v[186:189], v[232:235], v[18:21]
	v_mfma_f32_16x16x32_bf16 v[10:13], v[178:181], v[240:243], v[10:13]
	v_mfma_f32_16x16x32_bf16 v[2:5], v[186:189], v[240:243], v[2:5]
	v_mfma_f32_16x16x32_bf16 v[58:61], v[182:185], v[198:201], v[58:61]
	v_mfma_f32_16x16x32_bf16 v[50:53], v[190:193], v[198:201], v[50:53]
	v_mfma_f32_16x16x32_bf16 v[42:45], v[182:185], v[206:209], v[42:45]
	v_mfma_f32_16x16x32_bf16 v[34:37], v[190:193], v[206:209], v[34:37]
	v_mfma_f32_16x16x32_bf16 v[26:29], v[182:185], v[236:239], v[26:29]
	v_mfma_f32_16x16x32_bf16 v[18:21], v[190:193], v[236:239], v[18:21]
	v_mfma_f32_16x16x32_bf16 v[10:13], v[182:185], v[244:247], v[10:13]
	v_mfma_f32_16x16x32_bf16 v[2:5], v[190:193], v[244:247], v[2:5]
	s_setprio 0
	s_barrier
	s_add_i32 s55, 0, 0x18000
	v_add_u32_e32 v146, s55, v143
	s_add_i32 s56, 0, 0x1c000
	ds_read_b128 v[162:165], v146
	ds_read_b128 v[166:169], v146 offset:1024
	ds_read_b128 v[170:173], v146 offset:2048
	ds_read_b128 v[174:177], v146 offset:3072
	v_add_u32_e32 v146, s56, v143
	ds_read_b128 v[178:181], v146
	ds_read_b128 v[182:185], v146 offset:1024
	ds_read_b128 v[186:189], v146 offset:2048
	ds_read_b128 v[190:193], v146 offset:3072
	s_add_u32 s26, s26, 0x40000
	s_addc_u32 s27, s27, 0
	s_mov_b32 m0, s40
	v_lshl_add_u64 v[248:249], s[26:27], 0, v[134:135]
	ds_read_b128 v[194:197], v145 offset:32768
	ds_read_b128 v[198:201], v145 offset:33792
	ds_read_b128 v[202:205], v145 offset:34816
	ds_read_b128 v[206:209], v145 offset:35840
	ds_read_b128 v[232:235], v145 offset:36864
	ds_read_b128 v[236:239], v145 offset:37888
	ds_read_b128 v[240:243], v145 offset:38912
	ds_read_b128 v[244:247], v145 offset:39936
	global_load_lds_dwordx4 v[248:249], off
	v_lshl_add_u64 v[248:249], s[26:27], 0, v[132:133]
	s_mov_b32 m0, s41
	s_nop 0
	global_load_lds_dwordx4 v[248:249], off
	s_waitcnt vmcnt(8) lgkmcnt(0)
	s_barrier
	s_setprio 1
	v_mfma_f32_16x16x32_bf16 v[126:129], v[162:165], v[194:197], v[126:129]
	v_mfma_f32_16x16x32_bf16 v[118:121], v[170:173], v[194:197], v[118:121]
	v_mfma_f32_16x16x32_bf16 v[110:113], v[162:165], v[202:205], v[110:113]
	v_mfma_f32_16x16x32_bf16 v[102:105], v[170:173], v[202:205], v[102:105]
	v_mfma_f32_16x16x32_bf16 v[94:97], v[162:165], v[232:235], v[94:97]
	v_mfma_f32_16x16x32_bf16 v[86:89], v[170:173], v[232:235], v[86:89]
	v_mfma_f32_16x16x32_bf16 v[78:81], v[162:165], v[240:243], v[78:81]
	v_mfma_f32_16x16x32_bf16 v[70:73], v[170:173], v[240:243], v[70:73]
	v_mfma_f32_16x16x32_bf16 v[126:129], v[166:169], v[198:201], v[126:129]
	v_mfma_f32_16x16x32_bf16 v[118:121], v[174:177], v[198:201], v[118:121]
	v_mfma_f32_16x16x32_bf16 v[110:113], v[166:169], v[206:209], v[110:113]
	v_mfma_f32_16x16x32_bf16 v[102:105], v[174:177], v[206:209], v[102:105]
	v_mfma_f32_16x16x32_bf16 v[94:97], v[166:169], v[236:239], v[94:97]
	v_mfma_f32_16x16x32_bf16 v[86:89], v[174:177], v[236:239], v[86:89]
	v_mfma_f32_16x16x32_bf16 v[78:81], v[166:169], v[244:247], v[78:81]
	v_mfma_f32_16x16x32_bf16 v[70:73], v[174:177], v[244:247], v[70:73]
	v_mfma_f32_16x16x32_bf16 v[122:125], v[178:181], v[194:197], v[122:125]
	v_mfma_f32_16x16x32_bf16 v[114:117], v[186:189], v[194:197], v[114:117]
	v_mfma_f32_16x16x32_bf16 v[106:109], v[178:181], v[202:205], v[106:109]
	v_mfma_f32_16x16x32_bf16 v[98:101], v[186:189], v[202:205], v[98:101]
	v_mfma_f32_16x16x32_bf16 v[90:93], v[178:181], v[232:235], v[90:93]
	v_mfma_f32_16x16x32_bf16 v[82:85], v[186:189], v[232:235], v[82:85]
	v_mfma_f32_16x16x32_bf16 v[74:77], v[178:181], v[240:243], v[74:77]
	v_mfma_f32_16x16x32_bf16 v[66:69], v[186:189], v[240:243], v[66:69]
	v_mfma_f32_16x16x32_bf16 v[122:125], v[182:185], v[198:201], v[122:125]
	v_mfma_f32_16x16x32_bf16 v[114:117], v[190:193], v[198:201], v[114:117]
	v_mfma_f32_16x16x32_bf16 v[106:109], v[182:185], v[206:209], v[106:109]
	v_mfma_f32_16x16x32_bf16 v[98:101], v[190:193], v[206:209], v[98:101]
	v_mfma_f32_16x16x32_bf16 v[90:93], v[182:185], v[236:239], v[90:93]
	v_mfma_f32_16x16x32_bf16 v[82:85], v[190:193], v[236:239], v[82:85]
	v_mfma_f32_16x16x32_bf16 v[74:77], v[182:185], v[244:247], v[74:77]
	v_mfma_f32_16x16x32_bf16 v[66:69], v[190:193], v[244:247], v[66:69]
	s_setprio 0
	s_barrier
	s_add_i32 s26, s55, s36
	v_lshl_add_u64 v[140:141], v[140:141], 0, s[90:91]
	s_mov_b32 m0, s26
	ds_read_b128 v[194:197], v145 offset:49152
	ds_read_b128 v[198:201], v145 offset:50176
	ds_read_b128 v[202:205], v145 offset:51200
	ds_read_b128 v[206:209], v145 offset:52224
	ds_read_b128 v[232:235], v145 offset:53248
	ds_read_b128 v[236:239], v145 offset:54272
	ds_read_b128 v[240:243], v145 offset:55296
	ds_read_b128 v[244:247], v145 offset:56320
	global_load_lds_dwordx4 v[140:141], off
	s_add_i32 m0, s26, 0x2000
	s_add_u32 s24, s24, 0x40080
	v_lshl_add_u64 v[140:141], v[210:211], 0, s[90:91]
	s_addc_u32 s25, s25, 0
	s_add_i32 s26, s56, s36
	global_load_lds_dwordx4 v[140:141], off
	v_lshl_add_u64 v[140:141], s[24:25], 0, v[0:1]
	s_mov_b32 m0, s26
	s_nop 0
	global_load_lds_dwordx4 v[140:141], off
	v_lshl_add_u64 v[140:141], s[24:25], 0, v[130:131]
	s_add_i32 m0, s26, 0x2000
	s_nop 0
	global_load_lds_dwordx4 v[140:141], off
	v_lshl_add_u64 v[140:141], v[220:221], 0, s[90:91]
	s_mov_b32 m0, s42
	s_nop 0
	global_load_lds_dwordx4 v[140:141], off
	v_lshl_add_u64 v[140:141], v[222:223], 0, s[90:91]
	s_mov_b32 m0, s43
	s_nop 0
	global_load_lds_dwordx4 v[140:141], off
	s_waitcnt vmcnt(8) lgkmcnt(0)
	s_barrier
	s_setprio 1
	v_mfma_f32_16x16x32_bf16 v[62:65], v[162:165], v[194:197], v[62:65]
	v_mfma_f32_16x16x32_bf16 v[54:57], v[170:173], v[194:197], v[54:57]
	v_mfma_f32_16x16x32_bf16 v[46:49], v[162:165], v[202:205], v[46:49]
	v_mfma_f32_16x16x32_bf16 v[38:41], v[170:173], v[202:205], v[38:41]
	v_mfma_f32_16x16x32_bf16 v[30:33], v[162:165], v[232:235], v[30:33]
	v_mfma_f32_16x16x32_bf16 v[22:25], v[170:173], v[232:235], v[22:25]
	v_mfma_f32_16x16x32_bf16 v[14:17], v[162:165], v[240:243], v[14:17]
	v_mfma_f32_16x16x32_bf16 v[6:9], v[170:173], v[240:243], v[6:9]
	v_mfma_f32_16x16x32_bf16 v[62:65], v[166:169], v[198:201], v[62:65]
	v_mfma_f32_16x16x32_bf16 v[54:57], v[174:177], v[198:201], v[54:57]
	v_mfma_f32_16x16x32_bf16 v[46:49], v[166:169], v[206:209], v[46:49]
	v_mfma_f32_16x16x32_bf16 v[38:41], v[174:177], v[206:209], v[38:41]
	v_mfma_f32_16x16x32_bf16 v[30:33], v[166:169], v[236:239], v[30:33]
	v_mfma_f32_16x16x32_bf16 v[22:25], v[174:177], v[236:239], v[22:25]
	v_mfma_f32_16x16x32_bf16 v[14:17], v[166:169], v[244:247], v[14:17]
	v_mfma_f32_16x16x32_bf16 v[6:9], v[174:177], v[244:247], v[6:9]
	v_mfma_f32_16x16x32_bf16 v[58:61], v[178:181], v[194:197], v[58:61]
	v_mfma_f32_16x16x32_bf16 v[50:53], v[186:189], v[194:197], v[50:53]
	v_mfma_f32_16x16x32_bf16 v[42:45], v[178:181], v[202:205], v[42:45]
	v_mfma_f32_16x16x32_bf16 v[34:37], v[186:189], v[202:205], v[34:37]
	v_mfma_f32_16x16x32_bf16 v[26:29], v[178:181], v[232:235], v[26:29]
	v_mfma_f32_16x16x32_bf16 v[18:21], v[186:189], v[232:235], v[18:21]
	v_mfma_f32_16x16x32_bf16 v[10:13], v[178:181], v[240:243], v[10:13]
	v_mfma_f32_16x16x32_bf16 v[2:5], v[186:189], v[240:243], v[2:5]
	v_mfma_f32_16x16x32_bf16 v[58:61], v[182:185], v[198:201], v[58:61]
	v_mfma_f32_16x16x32_bf16 v[50:53], v[190:193], v[198:201], v[50:53]
	v_mfma_f32_16x16x32_bf16 v[42:45], v[182:185], v[206:209], v[42:45]
	v_mfma_f32_16x16x32_bf16 v[34:37], v[190:193], v[206:209], v[34:37]
	v_mfma_f32_16x16x32_bf16 v[26:29], v[182:185], v[236:239], v[26:29]
	v_mfma_f32_16x16x32_bf16 v[18:21], v[190:193], v[236:239], v[18:21]
	v_mfma_f32_16x16x32_bf16 v[10:13], v[182:185], v[244:247], v[10:13]
	v_mfma_f32_16x16x32_bf16 v[2:5], v[190:193], v[244:247], v[2:5]
	s_setprio 0
	s_barrier
	s_add_i32 s54, s54, 2
	s_add_u32 s22, s22, 0x100
	s_addc_u32 s23, s23, 0
	s_add_u32 s52, s52, 0x100
	s_addc_u32 s53, s53, 0
	s_cmp_gt_u32 s54, 13
	s_cbranch_scc0 .LBB0_194
	s_and_b64 vcc, exec, s[10:11]
	s_cbranch_vccz .LBB0_197
	s_barrier

.LBB0_274:
	s_add_u32 s16, s14, 0x100
	s_addc_u32 s17, s15, 0
	s_add_i32 s47, 0, 0x10000
	s_cmp_eq_u32 s46, 40
	s_cselect_b32 s21, s7, s17
	s_cselect_b32 s20, s6, s16
	v_add_u32_e32 v140, s47, v143
	s_cselect_b32 s19, s13, s45
	s_cselect_b32 s18, s12, s44
	s_add_i32 s52, 0, 0x14000
	ds_read_b128 v[136:139], v140
	ds_read_b128 v[162:165], v140 offset:1024
	ds_read_b128 v[166:169], v140 offset:2048
	ds_read_b128 v[170:173], v140 offset:3072
	v_add_u32_e32 v140, s52, v143
	ds_read_b128 v[174:177], v140
	ds_read_b128 v[178:181], v140 offset:1024
	ds_read_b128 v[182:185], v140 offset:2048
	ds_read_b128 v[186:189], v140 offset:3072
	v_lshl_add_u64 v[140:141], s[14:15], 0, v[132:133]
	s_add_i32 m0, s30, 0xc000
	ds_read_b128 v[190:193], v145
	ds_read_b128 v[194:197], v145 offset:1024
	ds_read_b128 v[198:201], v145 offset:2048
	ds_read_b128 v[202:205], v145 offset:3072
	ds_read_b128 v[206:209], v145 offset:4096
	ds_read_b128 v[232:235], v145 offset:5120
	ds_read_b128 v[236:239], v145 offset:6144
	ds_read_b128 v[240:243], v145 offset:7168
	global_load_lds_dwordx4 v[140:141], off
	v_lshl_add_u64 v[140:141], s[14:15], 0, v[134:135]
	s_add_i32 m0, s30, 0xe000
	s_nop 0
	global_load_lds_dwordx4 v[140:141], off
	s_waitcnt vmcnt(8) lgkmcnt(0)
	s_barrier
	s_setprio 1
	v_mfma_f32_16x16x32_bf16 v[126:129], v[136:139], v[190:193], v[126:129]
	v_mfma_f32_16x16x32_bf16 v[122:125], v[166:169], v[190:193], v[122:125]
	v_mfma_f32_16x16x32_bf16 v[110:113], v[136:139], v[198:201], v[110:113]
	v_mfma_f32_16x16x32_bf16 v[106:109], v[166:169], v[198:201], v[106:109]
	v_mfma_f32_16x16x32_bf16 v[94:97], v[136:139], v[206:209], v[94:97]
	v_mfma_f32_16x16x32_bf16 v[90:93], v[166:169], v[206:209], v[90:93]
	v_mfma_f32_16x16x32_bf16 v[78:81], v[136:139], v[236:239], v[78:81]
	v_mfma_f32_16x16x32_bf16 v[74:77], v[166:169], v[236:239], v[74:77]
	v_mfma_f32_16x16x32_bf16 v[126:129], v[162:165], v[194:197], v[126:129]
	v_mfma_f32_16x16x32_bf16 v[122:125], v[170:173], v[194:197], v[122:125]
	v_mfma_f32_16x16x32_bf16 v[110:113], v[162:165], v[202:205], v[110:113]
	v_mfma_f32_16x16x32_bf16 v[106:109], v[170:173], v[202:205], v[106:109]
	v_mfma_f32_16x16x32_bf16 v[94:97], v[162:165], v[232:235], v[94:97]
	v_mfma_f32_16x16x32_bf16 v[90:93], v[170:173], v[232:235], v[90:93]
	v_mfma_f32_16x16x32_bf16 v[78:81], v[162:165], v[240:243], v[78:81]
	v_mfma_f32_16x16x32_bf16 v[74:77], v[170:173], v[240:243], v[74:77]
	v_mfma_f32_16x16x32_bf16 v[118:121], v[174:177], v[190:193], v[118:121]
	v_mfma_f32_16x16x32_bf16 v[114:117], v[182:185], v[190:193], v[114:117]
	v_mfma_f32_16x16x32_bf16 v[102:105], v[174:177], v[198:201], v[102:105]
	v_mfma_f32_16x16x32_bf16 v[98:101], v[182:185], v[198:201], v[98:101]
	v_mfma_f32_16x16x32_bf16 v[86:89], v[174:177], v[206:209], v[86:89]
	v_mfma_f32_16x16x32_bf16 v[82:85], v[182:185], v[206:209], v[82:85]
	v_mfma_f32_16x16x32_bf16 v[70:73], v[174:177], v[236:239], v[70:73]
	v_mfma_f32_16x16x32_bf16 v[66:69], v[182:185], v[236:239], v[66:69]
	v_mfma_f32_16x16x32_bf16 v[118:121], v[178:181], v[194:197], v[118:121]
	v_mfma_f32_16x16x32_bf16 v[114:117], v[186:189], v[194:197], v[114:117]
	v_mfma_f32_16x16x32_bf16 v[102:105], v[178:181], v[202:205], v[102:105]
	v_mfma_f32_16x16x32_bf16 v[98:101], v[186:189], v[202:205], v[98:101]
	v_mfma_f32_16x16x32_bf16 v[86:89], v[178:181], v[232:235], v[86:89]
	v_mfma_f32_16x16x32_bf16 v[82:85], v[186:189], v[232:235], v[82:85]
	v_mfma_f32_16x16x32_bf16 v[70:73], v[178:181], v[240:243], v[70:73]
	v_mfma_f32_16x16x32_bf16 v[66:69], v[186:189], v[240:243], v[66:69]
	s_setprio 0
	s_barrier
	s_add_i32 s14, s47, s29
	v_lshl_add_u64 v[140:141], s[18:19], 0, v[0:1]
	s_mov_b32 m0, s14
	ds_read_b128 v[190:193], v145 offset:16384
	ds_read_b128 v[194:197], v145 offset:17408
	ds_read_b128 v[198:201], v145 offset:18432
	ds_read_b128 v[202:205], v145 offset:19456
	ds_read_b128 v[206:209], v145 offset:20480
	ds_read_b128 v[232:235], v145 offset:21504
	ds_read_b128 v[236:239], v145 offset:22528
	ds_read_b128 v[240:243], v145 offset:23552
	global_load_lds_dwordx4 v[140:141], off
	s_add_i32 m0, s14, 0x2000
	s_add_u32 s14, s18, 0xb0000
	v_lshl_add_u64 v[210:211], s[18:19], 0, v[130:131]
	s_addc_u32 s15, s19, 0
	s_add_i32 s47, s52, s29
	global_load_lds_dwordx4 v[210:211], off
	v_lshl_add_u64 v[220:221], s[14:15], 0, v[0:1]
	s_mov_b32 m0, s47
	v_lshl_add_u64 v[222:223], s[20:21], 0, v[130:131]
	global_load_lds_dwordx4 v[220:221], off
	v_lshl_add_u64 v[220:221], s[14:15], 0, v[130:131]
	s_add_i32 m0, s47, 0x2000
	s_nop 0
	global_load_lds_dwordx4 v[220:221], off
	v_lshl_add_u64 v[220:221], s[20:21], 0, v[0:1]
	s_mov_b32 m0, s30
	s_nop 0
	global_load_lds_dwordx4 v[220:221], off
	s_mov_b32 m0, s31
	s_nop 0
	global_load_lds_dwordx4 v[222:223], off
	s_waitcnt vmcnt(8) lgkmcnt(0)
	s_barrier
	s_setprio 1
	v_mfma_f32_16x16x32_bf16 v[62:65], v[136:139], v[190:193], v[62:65]
	v_mfma_f32_16x16x32_bf16 v[58:61], v[166:169], v[190:193], v[58:61]
	v_mfma_f32_16x16x32_bf16 v[46:49], v[136:139], v[198:201], v[46:49]
	v_mfma_f32_16x16x32_bf16 v[42:45], v[166:169], v[198:201], v[42:45]
	v_mfma_f32_16x16x32_bf16 v[30:33], v[136:139], v[206:209], v[30:33]
	v_mfma_f32_16x16x32_bf16 v[26:29], v[166:169], v[206:209], v[26:29]
	v_mfma_f32_16x16x32_bf16 v[14:17], v[136:139], v[236:239], v[14:17]
	v_mfma_f32_16x16x32_bf16 v[10:13], v[166:169], v[236:239], v[10:13]
	v_mfma_f32_16x16x32_bf16 v[62:65], v[162:165], v[194:197], v[62:65]
	v_mfma_f32_16x16x32_bf16 v[58:61], v[170:173], v[194:197], v[58:61]
	v_mfma_f32_16x16x32_bf16 v[46:49], v[162:165], v[202:205], v[46:49]
	v_mfma_f32_16x16x32_bf16 v[42:45], v[170:173], v[202:205], v[42:45]
	v_mfma_f32_16x16x32_bf16 v[30:33], v[162:165], v[232:235], v[30:33]
	v_mfma_f32_16x16x32_bf16 v[26:29], v[170:173], v[232:235], v[26:29]
	v_mfma_f32_16x16x32_bf16 v[14:17], v[162:165], v[240:243], v[14:17]
	v_mfma_f32_16x16x32_bf16 v[10:13], v[170:173], v[240:243], v[10:13]
	v_mfma_f32_16x16x32_bf16 v[54:57], v[174:177], v[190:193], v[54:57]
	v_mfma_f32_16x16x32_bf16 v[50:53], v[182:185], v[190:193], v[50:53]
	v_mfma_f32_16x16x32_bf16 v[38:41], v[174:177], v[198:201], v[38:41]
	v_mfma_f32_16x16x32_bf16 v[34:37], v[182:185], v[198:201], v[34:37]
	v_mfma_f32_16x16x32_bf16 v[22:25], v[174:177], v[206:209], v[22:25]
	v_mfma_f32_16x16x32_bf16 v[18:21], v[182:185], v[206:209], v[18:21]
	v_mfma_f32_16x16x32_bf16 v[6:9], v[174:177], v[236:239], v[6:9]
	v_mfma_f32_16x16x32_bf16 v[2:5], v[182:185], v[236:239], v[2:5]
	v_mfma_f32_16x16x32_bf16 v[54:57], v[178:181], v[194:197], v[54:57]
	v_mfma_f32_16x16x32_bf16 v[50:53], v[186:189], v[194:197], v[50:53]
	v_mfma_f32_16x16x32_bf16 v[38:41], v[178:181], v[202:205], v[38:41]
	v_mfma_f32_16x16x32_bf16 v[34:37], v[186:189], v[202:205], v[34:37]
	v_mfma_f32_16x16x32_bf16 v[22:25], v[178:181], v[232:235], v[22:25]
	v_mfma_f32_16x16x32_bf16 v[18:21], v[186:189], v[232:235], v[18:21]
	v_mfma_f32_16x16x32_bf16 v[6:9], v[178:181], v[240:243], v[6:9]
	v_mfma_f32_16x16x32_bf16 v[2:5], v[186:189], v[240:243], v[2:5]
	s_setprio 0
	s_barrier
	s_add_i32 s47, 0, 0x18000
	v_add_u32_e32 v146, s47, v143
	s_add_i32 s52, 0, 0x1c000
	ds_read_b128 v[136:139], v146
	ds_read_b128 v[162:165], v146 offset:1024
	ds_read_b128 v[166:169], v146 offset:2048
	ds_read_b128 v[170:173], v146 offset:3072
	v_add_u32_e32 v146, s52, v143
	ds_read_b128 v[174:177], v146
	ds_read_b128 v[178:181], v146 offset:1024
	ds_read_b128 v[182:185], v146 offset:2048
	ds_read_b128 v[186:189], v146 offset:3072
	s_add_u32 s14, s20, 0xb0000
	s_addc_u32 s15, s21, 0
	s_mov_b32 m0, s34
	v_lshl_add_u64 v[244:245], s[14:15], 0, v[0:1]
	ds_read_b128 v[190:193], v145 offset:32768
	ds_read_b128 v[194:197], v145 offset:33792
	ds_read_b128 v[198:201], v145 offset:34816
	ds_read_b128 v[202:205], v145 offset:35840
	ds_read_b128 v[206:209], v145 offset:36864
	ds_read_b128 v[232:235], v145 offset:37888
	ds_read_b128 v[236:239], v145 offset:38912
	ds_read_b128 v[240:243], v145 offset:39936
	global_load_lds_dwordx4 v[244:245], off
	v_lshl_add_u64 v[244:245], s[14:15], 0, v[130:131]
	s_mov_b32 m0, s35
	s_nop 0
	global_load_lds_dwordx4 v[244:245], off
	s_waitcnt vmcnt(8) lgkmcnt(0)
	s_barrier
	s_setprio 1
	v_mfma_f32_16x16x32_bf16 v[126:129], v[136:139], v[190:193], v[126:129]
	v_mfma_f32_16x16x32_bf16 v[122:125], v[166:169], v[190:193], v[122:125]
	v_mfma_f32_16x16x32_bf16 v[110:113], v[136:139], v[198:201], v[110:113]
	v_mfma_f32_16x16x32_bf16 v[106:109], v[166:169], v[198:201], v[106:109]
	v_mfma_f32_16x16x32_bf16 v[94:97], v[136:139], v[206:209], v[94:97]
	v_mfma_f32_16x16x32_bf16 v[90:93], v[166:169], v[206:209], v[90:93]
	v_mfma_f32_16x16x32_bf16 v[78:81], v[136:139], v[236:239], v[78:81]
	v_mfma_f32_16x16x32_bf16 v[74:77], v[166:169], v[236:239], v[74:77]
	v_mfma_f32_16x16x32_bf16 v[126:129], v[162:165], v[194:197], v[126:129]
	v_mfma_f32_16x16x32_bf16 v[122:125], v[170:173], v[194:197], v[122:125]
	v_mfma_f32_16x16x32_bf16 v[110:113], v[162:165], v[202:205], v[110:113]
	v_mfma_f32_16x16x32_bf16 v[106:109], v[170:173], v[202:205], v[106:109]
	v_mfma_f32_16x16x32_bf16 v[94:97], v[162:165], v[232:235], v[94:97]
	v_mfma_f32_16x16x32_bf16 v[90:93], v[170:173], v[232:235], v[90:93]
	v_mfma_f32_16x16x32_bf16 v[78:81], v[162:165], v[240:243], v[78:81]
	v_mfma_f32_16x16x32_bf16 v[74:77], v[170:173], v[240:243], v[74:77]
	v_mfma_f32_16x16x32_bf16 v[118:121], v[174:177], v[190:193], v[118:121]
	v_mfma_f32_16x16x32_bf16 v[114:117], v[182:185], v[190:193], v[114:117]
	v_mfma_f32_16x16x32_bf16 v[102:105], v[174:177], v[198:201], v[102:105]
	v_mfma_f32_16x16x32_bf16 v[98:101], v[182:185], v[198:201], v[98:101]
	v_mfma_f32_16x16x32_bf16 v[86:89], v[174:177], v[206:209], v[86:89]
	v_mfma_f32_16x16x32_bf16 v[82:85], v[182:185], v[206:209], v[82:85]
	v_mfma_f32_16x16x32_bf16 v[70:73], v[174:177], v[236:239], v[70:73]
	v_mfma_f32_16x16x32_bf16 v[66:69], v[182:185], v[236:239], v[66:69]
	v_mfma_f32_16x16x32_bf16 v[118:121], v[178:181], v[194:197], v[118:121]
	v_mfma_f32_16x16x32_bf16 v[114:117], v[186:189], v[194:197], v[114:117]
	v_mfma_f32_16x16x32_bf16 v[102:105], v[178:181], v[202:205], v[102:105]
	v_mfma_f32_16x16x32_bf16 v[98:101], v[186:189], v[202:205], v[98:101]
	v_mfma_f32_16x16x32_bf16 v[86:89], v[178:181], v[232:235], v[86:89]
	v_mfma_f32_16x16x32_bf16 v[82:85], v[186:189], v[232:235], v[82:85]
	v_mfma_f32_16x16x32_bf16 v[70:73], v[178:181], v[240:243], v[70:73]
	v_mfma_f32_16x16x32_bf16 v[66:69], v[186:189], v[240:243], v[66:69]
	s_setprio 0
	s_barrier
	s_add_i32 s14, s47, s29
	v_lshl_add_u64 v[140:141], v[140:141], 0, s[90:91]
	s_mov_b32 m0, s14
	ds_read_b128 v[190:193], v145 offset:49152
	ds_read_b128 v[194:197], v145 offset:50176
	ds_read_b128 v[198:201], v145 offset:51200
	ds_read_b128 v[202:205], v145 offset:52224
	ds_read_b128 v[206:209], v145 offset:53248
	ds_read_b128 v[232:235], v145 offset:54272
	ds_read_b128 v[236:239], v145 offset:55296
	ds_read_b128 v[240:243], v145 offset:56320
	global_load_lds_dwordx4 v[140:141], off
	s_add_i32 m0, s14, 0x2000
	s_add_u32 s14, s18, 0xb0080
	v_lshl_add_u64 v[140:141], v[210:211], 0, s[90:91]
	s_addc_u32 s15, s19, 0
	s_add_i32 s18, s52, s29
	global_load_lds_dwordx4 v[140:141], off
	v_lshl_add_u64 v[140:141], s[14:15], 0, v[0:1]
	s_mov_b32 m0, s18
	s_nop 0
	global_load_lds_dwordx4 v[140:141], off
	v_lshl_add_u64 v[140:141], s[14:15], 0, v[130:131]
	s_add_i32 m0, s18, 0x2000
	s_nop 0
	global_load_lds_dwordx4 v[140:141], off
	v_lshl_add_u64 v[140:141], v[220:221], 0, s[90:91]
	s_mov_b32 m0, s36
	s_nop 0
	global_load_lds_dwordx4 v[140:141], off
	v_lshl_add_u64 v[140:141], v[222:223], 0, s[90:91]
	s_mov_b32 m0, s37
	s_nop 0
	global_load_lds_dwordx4 v[140:141], off
	s_waitcnt vmcnt(8) lgkmcnt(0)
	s_barrier
	s_setprio 1
	v_mfma_f32_16x16x32_bf16 v[62:65], v[136:139], v[190:193], v[62:65]
	v_mfma_f32_16x16x32_bf16 v[58:61], v[166:169], v[190:193], v[58:61]
	v_mfma_f32_16x16x32_bf16 v[46:49], v[136:139], v[198:201], v[46:49]
	v_mfma_f32_16x16x32_bf16 v[42:45], v[166:169], v[198:201], v[42:45]
	v_mfma_f32_16x16x32_bf16 v[30:33], v[136:139], v[206:209], v[30:33]
	v_mfma_f32_16x16x32_bf16 v[26:29], v[166:169], v[206:209], v[26:29]
	v_mfma_f32_16x16x32_bf16 v[14:17], v[136:139], v[236:239], v[14:17]
	v_mfma_f32_16x16x32_bf16 v[10:13], v[166:169], v[236:239], v[10:13]
	v_mfma_f32_16x16x32_bf16 v[62:65], v[162:165], v[194:197], v[62:65]
	v_mfma_f32_16x16x32_bf16 v[58:61], v[170:173], v[194:197], v[58:61]
	v_mfma_f32_16x16x32_bf16 v[46:49], v[162:165], v[202:205], v[46:49]
	v_mfma_f32_16x16x32_bf16 v[42:45], v[170:173], v[202:205], v[42:45]
	v_mfma_f32_16x16x32_bf16 v[30:33], v[162:165], v[232:235], v[30:33]
	v_mfma_f32_16x16x32_bf16 v[26:29], v[170:173], v[232:235], v[26:29]
	v_mfma_f32_16x16x32_bf16 v[14:17], v[162:165], v[240:243], v[14:17]
	v_mfma_f32_16x16x32_bf16 v[10:13], v[170:173], v[240:243], v[10:13]
	v_mfma_f32_16x16x32_bf16 v[54:57], v[174:177], v[190:193], v[54:57]
	v_mfma_f32_16x16x32_bf16 v[50:53], v[182:185], v[190:193], v[50:53]
	v_mfma_f32_16x16x32_bf16 v[38:41], v[174:177], v[198:201], v[38:41]
	v_mfma_f32_16x16x32_bf16 v[34:37], v[182:185], v[198:201], v[34:37]
	v_mfma_f32_16x16x32_bf16 v[22:25], v[174:177], v[206:209], v[22:25]
	v_mfma_f32_16x16x32_bf16 v[18:21], v[182:185], v[206:209], v[18:21]
	v_mfma_f32_16x16x32_bf16 v[6:9], v[174:177], v[236:239], v[6:9]
	v_mfma_f32_16x16x32_bf16 v[2:5], v[182:185], v[236:239], v[2:5]
	v_mfma_f32_16x16x32_bf16 v[54:57], v[178:181], v[194:197], v[54:57]
	v_mfma_f32_16x16x32_bf16 v[50:53], v[186:189], v[194:197], v[50:53]
	v_mfma_f32_16x16x32_bf16 v[38:41], v[178:181], v[202:205], v[38:41]
	v_mfma_f32_16x16x32_bf16 v[34:37], v[186:189], v[202:205], v[34:37]
	v_mfma_f32_16x16x32_bf16 v[22:25], v[178:181], v[232:235], v[22:25]
	v_mfma_f32_16x16x32_bf16 v[18:21], v[186:189], v[232:235], v[18:21]
	v_mfma_f32_16x16x32_bf16 v[6:9], v[178:181], v[240:243], v[6:9]
	v_mfma_f32_16x16x32_bf16 v[2:5], v[186:189], v[240:243], v[2:5]
	s_setprio 0
	s_barrier
	s_add_i32 s46, s46, 2
	s_add_u32 s44, s44, 0x100
	s_addc_u32 s45, s45, 0
	s_cmp_gt_u32 s46, 41
	s_mov_b64 s[14:15], s[16:17]
	s_cbranch_scc0 .LBB0_274
	s_and_b64 vcc, exec, s[10:11]
	s_cbranch_vccz .LBB0_277
	s_barrier

.LBB0_405:
	s_add_u32 s30, s28, 0xfffc0080
	s_addc_u32 s31, s29, -1
	s_add_i32 s56, 0, 0x10000
	s_cmp_eq_u32 s75, 12
	s_cselect_b32 s35, s21, s31
	s_cselect_b32 s34, s71, s30
	v_add_u32_e32 v140, s56, v143
	s_cselect_b32 s31, s19, s74
	s_cselect_b32 s30, s72, s73
	s_add_i32 s76, 0, 0x14000
	ds_read_b128 v[162:165], v140
	ds_read_b128 v[166:169], v140 offset:1024
	ds_read_b128 v[170:173], v140 offset:2048
	ds_read_b128 v[174:177], v140 offset:3072
	v_add_u32_e32 v140, s76, v143
	ds_read_b128 v[178:181], v140
	ds_read_b128 v[182:185], v140 offset:1024
	ds_read_b128 v[186:189], v140 offset:2048
	ds_read_b128 v[190:193], v140 offset:3072
	v_lshl_add_u64 v[140:141], s[28:29], 0, v[136:137]
	s_add_i32 m0, s25, 0xc000
	ds_read_b128 v[194:197], v145
	ds_read_b128 v[198:201], v145 offset:1024
	ds_read_b128 v[202:205], v145 offset:2048
	ds_read_b128 v[206:209], v145 offset:3072
	ds_read_b128 v[232:235], v145 offset:4096
	ds_read_b128 v[236:239], v145 offset:5120
	ds_read_b128 v[240:243], v145 offset:6144
	ds_read_b128 v[244:247], v145 offset:7168
	global_load_lds_dwordx4 v[140:141], off
	v_lshl_add_u64 v[140:141], s[28:29], 0, v[138:139]
	s_add_i32 m0, s25, 0xe000
	s_nop 0
	global_load_lds_dwordx4 v[140:141], off
	s_waitcnt vmcnt(8) lgkmcnt(0)
	s_barrier
	s_setprio 1
	v_mfma_f32_16x16x32_bf16 v[126:129], v[162:165], v[194:197], v[126:129]
	v_mfma_f32_16x16x32_bf16 v[122:125], v[170:173], v[194:197], v[122:125]
	v_mfma_f32_16x16x32_bf16 v[118:121], v[162:165], v[202:205], v[118:121]
	v_mfma_f32_16x16x32_bf16 v[110:113], v[170:173], v[202:205], v[110:113]
	v_mfma_f32_16x16x32_bf16 v[102:105], v[162:165], v[232:235], v[102:105]
	v_mfma_f32_16x16x32_bf16 v[94:97], v[170:173], v[232:235], v[94:97]
	v_mfma_f32_16x16x32_bf16 v[86:89], v[162:165], v[240:243], v[86:89]
	v_mfma_f32_16x16x32_bf16 v[78:81], v[170:173], v[240:243], v[78:81]
	v_mfma_f32_16x16x32_bf16 v[126:129], v[166:169], v[198:201], v[126:129]
	v_mfma_f32_16x16x32_bf16 v[122:125], v[174:177], v[198:201], v[122:125]
	v_mfma_f32_16x16x32_bf16 v[118:121], v[166:169], v[206:209], v[118:121]
	v_mfma_f32_16x16x32_bf16 v[110:113], v[174:177], v[206:209], v[110:113]
	v_mfma_f32_16x16x32_bf16 v[102:105], v[166:169], v[236:239], v[102:105]
	v_mfma_f32_16x16x32_bf16 v[94:97], v[174:177], v[236:239], v[94:97]
	v_mfma_f32_16x16x32_bf16 v[86:89], v[166:169], v[244:247], v[86:89]
	v_mfma_f32_16x16x32_bf16 v[78:81], v[174:177], v[244:247], v[78:81]
	v_mfma_f32_16x16x32_bf16 v[114:117], v[178:181], v[194:197], v[114:117]
	v_mfma_f32_16x16x32_bf16 v[106:109], v[186:189], v[194:197], v[106:109]
	v_mfma_f32_16x16x32_bf16 v[98:101], v[178:181], v[202:205], v[98:101]
	v_mfma_f32_16x16x32_bf16 v[90:93], v[186:189], v[202:205], v[90:93]
	v_mfma_f32_16x16x32_bf16 v[82:85], v[178:181], v[232:235], v[82:85]
	v_mfma_f32_16x16x32_bf16 v[74:77], v[186:189], v[232:235], v[74:77]
	v_mfma_f32_16x16x32_bf16 v[70:73], v[178:181], v[240:243], v[70:73]
	v_mfma_f32_16x16x32_bf16 v[66:69], v[186:189], v[240:243], v[66:69]
	v_mfma_f32_16x16x32_bf16 v[114:117], v[182:185], v[198:201], v[114:117]
	v_mfma_f32_16x16x32_bf16 v[106:109], v[190:193], v[198:201], v[106:109]
	v_mfma_f32_16x16x32_bf16 v[98:101], v[182:185], v[206:209], v[98:101]
	v_mfma_f32_16x16x32_bf16 v[90:93], v[190:193], v[206:209], v[90:93]
	v_mfma_f32_16x16x32_bf16 v[82:85], v[182:185], v[236:239], v[82:85]
	v_mfma_f32_16x16x32_bf16 v[74:77], v[190:193], v[236:239], v[74:77]
	v_mfma_f32_16x16x32_bf16 v[70:73], v[182:185], v[244:247], v[70:73]
	v_mfma_f32_16x16x32_bf16 v[66:69], v[190:193], v[244:247], v[66:69]
	s_setprio 0
	s_barrier
	s_add_i32 s56, s56, s13
	v_lshl_add_u64 v[140:141], s[30:31], 0, v[0:1]
	s_mov_b32 m0, s56
	ds_read_b128 v[194:197], v145 offset:16384
	ds_read_b128 v[198:201], v145 offset:17408
	ds_read_b128 v[202:205], v145 offset:18432
	ds_read_b128 v[206:209], v145 offset:19456
	ds_read_b128 v[232:235], v145 offset:20480
	ds_read_b128 v[236:239], v145 offset:21504
	ds_read_b128 v[240:243], v145 offset:22528
	ds_read_b128 v[244:247], v145 offset:23552
	global_load_lds_dwordx4 v[140:141], off
	s_add_i32 m0, s56, 0x2000
	s_add_u32 s56, s30, 0x40000
	v_lshl_add_u64 v[210:211], s[30:31], 0, v[130:131]
	s_addc_u32 s57, s31, 0
	s_add_i32 s76, s76, s13
	global_load_lds_dwordx4 v[210:211], off
	v_lshl_add_u64 v[220:221], s[56:57], 0, v[0:1]
	s_mov_b32 m0, s76
	v_lshl_add_u64 v[222:223], s[34:35], 0, v[132:133]
	global_load_lds_dwordx4 v[220:221], off
	v_lshl_add_u64 v[220:221], s[56:57], 0, v[130:131]
	s_add_i32 m0, s76, 0x2000
	s_nop 0
	global_load_lds_dwordx4 v[220:221], off
	v_lshl_add_u64 v[220:221], s[34:35], 0, v[134:135]
	s_mov_b32 m0, s25
	s_nop 0
	global_load_lds_dwordx4 v[220:221], off
	s_mov_b32 m0, s47
	s_nop 0
	global_load_lds_dwordx4 v[222:223], off
	s_waitcnt vmcnt(8) lgkmcnt(0)
	s_barrier
	s_setprio 1
	v_mfma_f32_16x16x32_bf16 v[62:65], v[162:165], v[194:197], v[62:65]
	v_mfma_f32_16x16x32_bf16 v[58:61], v[170:173], v[194:197], v[58:61]
	v_mfma_f32_16x16x32_bf16 v[54:57], v[162:165], v[202:205], v[54:57]
	v_mfma_f32_16x16x32_bf16 v[46:49], v[170:173], v[202:205], v[46:49]
	v_mfma_f32_16x16x32_bf16 v[38:41], v[162:165], v[232:235], v[38:41]
	v_mfma_f32_16x16x32_bf16 v[30:33], v[170:173], v[232:235], v[30:33]
	v_mfma_f32_16x16x32_bf16 v[22:25], v[162:165], v[240:243], v[22:25]
	v_mfma_f32_16x16x32_bf16 v[14:17], v[170:173], v[240:243], v[14:17]
	v_mfma_f32_16x16x32_bf16 v[62:65], v[166:169], v[198:201], v[62:65]
	v_mfma_f32_16x16x32_bf16 v[58:61], v[174:177], v[198:201], v[58:61]
	v_mfma_f32_16x16x32_bf16 v[54:57], v[166:169], v[206:209], v[54:57]
	v_mfma_f32_16x16x32_bf16 v[46:49], v[174:177], v[206:209], v[46:49]
	v_mfma_f32_16x16x32_bf16 v[38:41], v[166:169], v[236:239], v[38:41]
	v_mfma_f32_16x16x32_bf16 v[30:33], v[174:177], v[236:239], v[30:33]
	v_mfma_f32_16x16x32_bf16 v[22:25], v[166:169], v[244:247], v[22:25]
	v_mfma_f32_16x16x32_bf16 v[14:17], v[174:177], v[244:247], v[14:17]
	v_mfma_f32_16x16x32_bf16 v[50:53], v[178:181], v[194:197], v[50:53]
	v_mfma_f32_16x16x32_bf16 v[42:45], v[186:189], v[194:197], v[42:45]
	v_mfma_f32_16x16x32_bf16 v[34:37], v[178:181], v[202:205], v[34:37]
	v_mfma_f32_16x16x32_bf16 v[26:29], v[186:189], v[202:205], v[26:29]
	v_mfma_f32_16x16x32_bf16 v[18:21], v[178:181], v[232:235], v[18:21]
	v_mfma_f32_16x16x32_bf16 v[10:13], v[186:189], v[232:235], v[10:13]
	v_mfma_f32_16x16x32_bf16 v[6:9], v[178:181], v[240:243], v[6:9]
	v_mfma_f32_16x16x32_bf16 v[2:5], v[186:189], v[240:243], v[2:5]
	v_mfma_f32_16x16x32_bf16 v[50:53], v[182:185], v[198:201], v[50:53]
	v_mfma_f32_16x16x32_bf16 v[42:45], v[190:193], v[198:201], v[42:45]
	v_mfma_f32_16x16x32_bf16 v[34:37], v[182:185], v[206:209], v[34:37]
	v_mfma_f32_16x16x32_bf16 v[26:29], v[190:193], v[206:209], v[26:29]
	v_mfma_f32_16x16x32_bf16 v[18:21], v[182:185], v[236:239], v[18:21]
	v_mfma_f32_16x16x32_bf16 v[10:13], v[190:193], v[236:239], v[10:13]
	v_mfma_f32_16x16x32_bf16 v[6:9], v[182:185], v[244:247], v[6:9]
	v_mfma_f32_16x16x32_bf16 v[2:5], v[190:193], v[244:247], v[2:5]
	s_setprio 0
	s_barrier
	s_add_i32 s56, 0, 0x18000
	v_add_u32_e32 v146, s56, v143
	s_add_i32 s57, 0, 0x1c000
	ds_read_b128 v[162:165], v146
	ds_read_b128 v[166:169], v146 offset:1024
	ds_read_b128 v[170:173], v146 offset:2048
	ds_read_b128 v[174:177], v146 offset:3072
	v_add_u32_e32 v146, s57, v143
	ds_read_b128 v[178:181], v146
	ds_read_b128 v[182:185], v146 offset:1024
	ds_read_b128 v[186:189], v146 offset:2048
	ds_read_b128 v[190:193], v146 offset:3072
	s_add_u32 s34, s34, 0x40000
	s_addc_u32 s35, s35, 0
	s_mov_b32 m0, s52
	v_lshl_add_u64 v[248:249], s[34:35], 0, v[134:135]
	ds_read_b128 v[194:197], v145 offset:32768
	ds_read_b128 v[198:201], v145 offset:33792
	ds_read_b128 v[202:205], v145 offset:34816
	ds_read_b128 v[206:209], v145 offset:35840
	ds_read_b128 v[232:235], v145 offset:36864
	ds_read_b128 v[236:239], v145 offset:37888
	ds_read_b128 v[240:243], v145 offset:38912
	ds_read_b128 v[244:247], v145 offset:39936
	global_load_lds_dwordx4 v[248:249], off
	v_lshl_add_u64 v[248:249], s[34:35], 0, v[132:133]
	s_mov_b32 m0, s53
	s_nop 0
	global_load_lds_dwordx4 v[248:249], off
	s_waitcnt vmcnt(8) lgkmcnt(0)
	s_barrier
	s_setprio 1
	v_mfma_f32_16x16x32_bf16 v[126:129], v[162:165], v[194:197], v[126:129]
	v_mfma_f32_16x16x32_bf16 v[122:125], v[170:173], v[194:197], v[122:125]
	v_mfma_f32_16x16x32_bf16 v[118:121], v[162:165], v[202:205], v[118:121]
	v_mfma_f32_16x16x32_bf16 v[110:113], v[170:173], v[202:205], v[110:113]
	v_mfma_f32_16x16x32_bf16 v[102:105], v[162:165], v[232:235], v[102:105]
	v_mfma_f32_16x16x32_bf16 v[94:97], v[170:173], v[232:235], v[94:97]
	v_mfma_f32_16x16x32_bf16 v[86:89], v[162:165], v[240:243], v[86:89]
	v_mfma_f32_16x16x32_bf16 v[78:81], v[170:173], v[240:243], v[78:81]
	v_mfma_f32_16x16x32_bf16 v[126:129], v[166:169], v[198:201], v[126:129]
	v_mfma_f32_16x16x32_bf16 v[122:125], v[174:177], v[198:201], v[122:125]
	v_mfma_f32_16x16x32_bf16 v[118:121], v[166:169], v[206:209], v[118:121]
	v_mfma_f32_16x16x32_bf16 v[110:113], v[174:177], v[206:209], v[110:113]
	v_mfma_f32_16x16x32_bf16 v[102:105], v[166:169], v[236:239], v[102:105]
	v_mfma_f32_16x16x32_bf16 v[94:97], v[174:177], v[236:239], v[94:97]
	v_mfma_f32_16x16x32_bf16 v[86:89], v[166:169], v[244:247], v[86:89]
	v_mfma_f32_16x16x32_bf16 v[78:81], v[174:177], v[244:247], v[78:81]
	v_mfma_f32_16x16x32_bf16 v[114:117], v[178:181], v[194:197], v[114:117]
	v_mfma_f32_16x16x32_bf16 v[106:109], v[186:189], v[194:197], v[106:109]
	v_mfma_f32_16x16x32_bf16 v[98:101], v[178:181], v[202:205], v[98:101]
	v_mfma_f32_16x16x32_bf16 v[90:93], v[186:189], v[202:205], v[90:93]
	v_mfma_f32_16x16x32_bf16 v[82:85], v[178:181], v[232:235], v[82:85]
	v_mfma_f32_16x16x32_bf16 v[74:77], v[186:189], v[232:235], v[74:77]
	v_mfma_f32_16x16x32_bf16 v[70:73], v[178:181], v[240:243], v[70:73]
	v_mfma_f32_16x16x32_bf16 v[66:69], v[186:189], v[240:243], v[66:69]
	v_mfma_f32_16x16x32_bf16 v[114:117], v[182:185], v[198:201], v[114:117]
	v_mfma_f32_16x16x32_bf16 v[106:109], v[190:193], v[198:201], v[106:109]
	v_mfma_f32_16x16x32_bf16 v[98:101], v[182:185], v[206:209], v[98:101]
	v_mfma_f32_16x16x32_bf16 v[90:93], v[190:193], v[206:209], v[90:93]
	v_mfma_f32_16x16x32_bf16 v[82:85], v[182:185], v[236:239], v[82:85]
	v_mfma_f32_16x16x32_bf16 v[74:77], v[190:193], v[236:239], v[74:77]
	v_mfma_f32_16x16x32_bf16 v[70:73], v[182:185], v[244:247], v[70:73]
	v_mfma_f32_16x16x32_bf16 v[66:69], v[190:193], v[244:247], v[66:69]
	s_setprio 0
	s_barrier
	s_add_i32 s34, s56, s13
	v_lshl_add_u64 v[140:141], v[140:141], 0, s[90:91]
	s_mov_b32 m0, s34
	ds_read_b128 v[194:197], v145 offset:49152
	ds_read_b128 v[198:201], v145 offset:50176
	ds_read_b128 v[202:205], v145 offset:51200
	ds_read_b128 v[206:209], v145 offset:52224
	ds_read_b128 v[232:235], v145 offset:53248
	ds_read_b128 v[236:239], v145 offset:54272
	ds_read_b128 v[240:243], v145 offset:55296
	ds_read_b128 v[244:247], v145 offset:56320
	global_load_lds_dwordx4 v[140:141], off
	s_add_i32 m0, s34, 0x2000
	s_add_u32 s30, s30, 0x40080
	v_lshl_add_u64 v[140:141], v[210:211], 0, s[90:91]
	s_addc_u32 s31, s31, 0
	s_add_i32 s34, s57, s13
	global_load_lds_dwordx4 v[140:141], off
	v_lshl_add_u64 v[140:141], s[30:31], 0, v[0:1]
	s_mov_b32 m0, s34
	s_nop 0
	global_load_lds_dwordx4 v[140:141], off
	v_lshl_add_u64 v[140:141], s[30:31], 0, v[130:131]
	s_add_i32 m0, s34, 0x2000
	s_nop 0
	global_load_lds_dwordx4 v[140:141], off
	v_lshl_add_u64 v[140:141], v[220:221], 0, s[90:91]
	s_mov_b32 m0, s54
	s_nop 0
	global_load_lds_dwordx4 v[140:141], off
	v_lshl_add_u64 v[140:141], v[222:223], 0, s[90:91]
	s_mov_b32 m0, s55
	s_nop 0
	global_load_lds_dwordx4 v[140:141], off
	s_waitcnt vmcnt(8) lgkmcnt(0)
	s_barrier
	s_setprio 1
	v_mfma_f32_16x16x32_bf16 v[62:65], v[162:165], v[194:197], v[62:65]
	v_mfma_f32_16x16x32_bf16 v[58:61], v[170:173], v[194:197], v[58:61]
	v_mfma_f32_16x16x32_bf16 v[54:57], v[162:165], v[202:205], v[54:57]
	v_mfma_f32_16x16x32_bf16 v[46:49], v[170:173], v[202:205], v[46:49]
	v_mfma_f32_16x16x32_bf16 v[38:41], v[162:165], v[232:235], v[38:41]
	v_mfma_f32_16x16x32_bf16 v[30:33], v[170:173], v[232:235], v[30:33]
	v_mfma_f32_16x16x32_bf16 v[22:25], v[162:165], v[240:243], v[22:25]
	v_mfma_f32_16x16x32_bf16 v[14:17], v[170:173], v[240:243], v[14:17]
	v_mfma_f32_16x16x32_bf16 v[62:65], v[166:169], v[198:201], v[62:65]
	v_mfma_f32_16x16x32_bf16 v[58:61], v[174:177], v[198:201], v[58:61]
	v_mfma_f32_16x16x32_bf16 v[54:57], v[166:169], v[206:209], v[54:57]
	v_mfma_f32_16x16x32_bf16 v[46:49], v[174:177], v[206:209], v[46:49]
	v_mfma_f32_16x16x32_bf16 v[38:41], v[166:169], v[236:239], v[38:41]
	v_mfma_f32_16x16x32_bf16 v[30:33], v[174:177], v[236:239], v[30:33]
	v_mfma_f32_16x16x32_bf16 v[22:25], v[166:169], v[244:247], v[22:25]
	v_mfma_f32_16x16x32_bf16 v[14:17], v[174:177], v[244:247], v[14:17]
	v_mfma_f32_16x16x32_bf16 v[50:53], v[178:181], v[194:197], v[50:53]
	v_mfma_f32_16x16x32_bf16 v[42:45], v[186:189], v[194:197], v[42:45]
	v_mfma_f32_16x16x32_bf16 v[34:37], v[178:181], v[202:205], v[34:37]
	v_mfma_f32_16x16x32_bf16 v[26:29], v[186:189], v[202:205], v[26:29]
	v_mfma_f32_16x16x32_bf16 v[18:21], v[178:181], v[232:235], v[18:21]
	v_mfma_f32_16x16x32_bf16 v[10:13], v[186:189], v[232:235], v[10:13]
	v_mfma_f32_16x16x32_bf16 v[6:9], v[178:181], v[240:243], v[6:9]
	v_mfma_f32_16x16x32_bf16 v[2:5], v[186:189], v[240:243], v[2:5]
	v_mfma_f32_16x16x32_bf16 v[50:53], v[182:185], v[198:201], v[50:53]
	v_mfma_f32_16x16x32_bf16 v[42:45], v[190:193], v[198:201], v[42:45]
	v_mfma_f32_16x16x32_bf16 v[34:37], v[182:185], v[206:209], v[34:37]
	v_mfma_f32_16x16x32_bf16 v[26:29], v[190:193], v[206:209], v[26:29]
	v_mfma_f32_16x16x32_bf16 v[18:21], v[182:185], v[236:239], v[18:21]
	v_mfma_f32_16x16x32_bf16 v[10:13], v[190:193], v[236:239], v[10:13]
	v_mfma_f32_16x16x32_bf16 v[6:9], v[182:185], v[244:247], v[6:9]
	v_mfma_f32_16x16x32_bf16 v[2:5], v[190:193], v[244:247], v[2:5]
	s_setprio 0
	s_barrier
	s_add_i32 s75, s75, 2
	s_add_u32 s28, s28, 0x100
	s_addc_u32 s29, s29, 0
	s_add_u32 s73, s73, 0x100
	s_addc_u32 s74, s74, 0
	s_cmp_gt_u32 s75, 13
	s_cbranch_scc0 .LBB0_405
	s_and_b64 vcc, exec, s[16:17]
	s_cbranch_vccz .LBB0_408
	s_barrier

.LBB0_546:
	s_add_u32 s18, s16, 0x100
	s_addc_u32 s19, s17, 0
	s_add_i32 s53, 0, 0x10000
	s_cmp_eq_u32 s52, 2
	s_cselect_b32 s23, s7, s19
	s_cselect_b32 s22, s6, s18
	v_add_u32_e32 v144, s53, v141
	s_cselect_b32 s21, s15, s47
	s_cselect_b32 s20, s14, s46
	s_add_i32 s54, 0, 0x14000
	ds_read_b128 v[162:165], v144
	ds_read_b128 v[166:169], v144 offset:1024
	ds_read_b128 v[170:173], v144 offset:2048
	ds_read_b128 v[174:177], v144 offset:3072
	v_add_u32_e32 v144, s54, v141
	ds_read_b128 v[178:181], v144
	ds_read_b128 v[182:185], v144 offset:1024
	ds_read_b128 v[186:189], v144 offset:2048
	ds_read_b128 v[190:193], v144 offset:3072
	v_lshl_add_u64 v[144:145], s[16:17], 0, v[136:137]
	s_add_i32 m0, s34, 0xc000
	ds_read_b128 v[194:197], v143
	ds_read_b128 v[198:201], v143 offset:1024
	ds_read_b128 v[202:205], v143 offset:2048
	ds_read_b128 v[206:209], v143 offset:3072
	ds_read_b128 v[232:235], v143 offset:4096
	ds_read_b128 v[236:239], v143 offset:5120
	ds_read_b128 v[240:243], v143 offset:6144
	ds_read_b128 v[244:247], v143 offset:7168
	global_load_lds_dwordx4 v[144:145], off
	v_lshl_add_u64 v[144:145], s[16:17], 0, v[138:139]
	s_add_i32 m0, s34, 0xe000
	s_nop 0
	global_load_lds_dwordx4 v[144:145], off
	s_waitcnt vmcnt(8) lgkmcnt(0)
	s_barrier
	s_setprio 1
	v_mfma_f32_16x16x32_bf16 v[126:129], v[162:165], v[194:197], v[126:129]
	v_mfma_f32_16x16x32_bf16 v[122:125], v[170:173], v[194:197], v[122:125]
	v_mfma_f32_16x16x32_bf16 v[118:121], v[162:165], v[202:205], v[118:121]
	v_mfma_f32_16x16x32_bf16 v[110:113], v[170:173], v[202:205], v[110:113]
	v_mfma_f32_16x16x32_bf16 v[102:105], v[162:165], v[232:235], v[102:105]
	v_mfma_f32_16x16x32_bf16 v[94:97], v[170:173], v[232:235], v[94:97]
	v_mfma_f32_16x16x32_bf16 v[86:89], v[162:165], v[240:243], v[86:89]
	v_mfma_f32_16x16x32_bf16 v[78:81], v[170:173], v[240:243], v[78:81]
	v_mfma_f32_16x16x32_bf16 v[126:129], v[166:169], v[198:201], v[126:129]
	v_mfma_f32_16x16x32_bf16 v[122:125], v[174:177], v[198:201], v[122:125]
	v_mfma_f32_16x16x32_bf16 v[118:121], v[166:169], v[206:209], v[118:121]
	v_mfma_f32_16x16x32_bf16 v[110:113], v[174:177], v[206:209], v[110:113]
	v_mfma_f32_16x16x32_bf16 v[102:105], v[166:169], v[236:239], v[102:105]
	v_mfma_f32_16x16x32_bf16 v[94:97], v[174:177], v[236:239], v[94:97]
	v_mfma_f32_16x16x32_bf16 v[86:89], v[166:169], v[244:247], v[86:89]
	v_mfma_f32_16x16x32_bf16 v[78:81], v[174:177], v[244:247], v[78:81]
	v_mfma_f32_16x16x32_bf16 v[114:117], v[178:181], v[194:197], v[114:117]
	v_mfma_f32_16x16x32_bf16 v[106:109], v[186:189], v[194:197], v[106:109]
	v_mfma_f32_16x16x32_bf16 v[98:101], v[178:181], v[202:205], v[98:101]
	v_mfma_f32_16x16x32_bf16 v[90:93], v[186:189], v[202:205], v[90:93]
	v_mfma_f32_16x16x32_bf16 v[82:85], v[178:181], v[232:235], v[82:85]
	v_mfma_f32_16x16x32_bf16 v[74:77], v[186:189], v[232:235], v[74:77]
	v_mfma_f32_16x16x32_bf16 v[70:73], v[178:181], v[240:243], v[70:73]
	v_mfma_f32_16x16x32_bf16 v[66:69], v[186:189], v[240:243], v[66:69]
	v_mfma_f32_16x16x32_bf16 v[114:117], v[182:185], v[198:201], v[114:117]
	v_mfma_f32_16x16x32_bf16 v[106:109], v[190:193], v[198:201], v[106:109]
	v_mfma_f32_16x16x32_bf16 v[98:101], v[182:185], v[206:209], v[98:101]
	v_mfma_f32_16x16x32_bf16 v[90:93], v[190:193], v[206:209], v[90:93]
	v_mfma_f32_16x16x32_bf16 v[82:85], v[182:185], v[236:239], v[82:85]
	v_mfma_f32_16x16x32_bf16 v[74:77], v[190:193], v[236:239], v[74:77]
	v_mfma_f32_16x16x32_bf16 v[70:73], v[182:185], v[244:247], v[70:73]
	v_mfma_f32_16x16x32_bf16 v[66:69], v[190:193], v[244:247], v[66:69]
	s_setprio 0
	s_barrier
	s_add_i32 s16, s53, s30
	v_lshl_add_u64 v[144:145], s[20:21], 0, v[0:1]
	s_mov_b32 m0, s16
	ds_read_b128 v[194:197], v143 offset:16384
	ds_read_b128 v[198:201], v143 offset:17408
	ds_read_b128 v[202:205], v143 offset:18432
	ds_read_b128 v[206:209], v143 offset:19456
	ds_read_b128 v[232:235], v143 offset:20480
	ds_read_b128 v[236:239], v143 offset:21504
	ds_read_b128 v[240:243], v143 offset:22528
	ds_read_b128 v[244:247], v143 offset:23552
	global_load_lds_dwordx4 v[144:145], off
	s_add_i32 m0, s16, 0x2000
	s_add_u32 s16, s20, 0x18000
	v_lshl_add_u64 v[210:211], s[20:21], 0, v[130:131]
	s_addc_u32 s17, s21, 0
	s_add_i32 s53, s54, s30
	global_load_lds_dwordx4 v[210:211], off
	v_lshl_add_u64 v[220:221], s[16:17], 0, v[0:1]
	s_mov_b32 m0, s53
	v_lshl_add_u64 v[222:223], s[22:23], 0, v[132:133]
	global_load_lds_dwordx4 v[220:221], off
	v_lshl_add_u64 v[220:221], s[16:17], 0, v[130:131]
	s_add_i32 m0, s53, 0x2000
	s_nop 0
	global_load_lds_dwordx4 v[220:221], off
	v_lshl_add_u64 v[220:221], s[22:23], 0, v[134:135]
	s_mov_b32 m0, s34
	s_nop 0
	global_load_lds_dwordx4 v[220:221], off
	s_mov_b32 m0, s35
	s_nop 0
	global_load_lds_dwordx4 v[222:223], off
	s_waitcnt vmcnt(8) lgkmcnt(0)
	s_barrier
	s_setprio 1
	v_mfma_f32_16x16x32_bf16 v[62:65], v[162:165], v[194:197], v[62:65]
	v_mfma_f32_16x16x32_bf16 v[58:61], v[170:173], v[194:197], v[58:61]
	v_mfma_f32_16x16x32_bf16 v[54:57], v[162:165], v[202:205], v[54:57]
	v_mfma_f32_16x16x32_bf16 v[46:49], v[170:173], v[202:205], v[46:49]
	v_mfma_f32_16x16x32_bf16 v[38:41], v[162:165], v[232:235], v[38:41]
	v_mfma_f32_16x16x32_bf16 v[30:33], v[170:173], v[232:235], v[30:33]
	v_mfma_f32_16x16x32_bf16 v[22:25], v[162:165], v[240:243], v[22:25]
	v_mfma_f32_16x16x32_bf16 v[14:17], v[170:173], v[240:243], v[14:17]
	v_mfma_f32_16x16x32_bf16 v[62:65], v[166:169], v[198:201], v[62:65]
	v_mfma_f32_16x16x32_bf16 v[58:61], v[174:177], v[198:201], v[58:61]
	v_mfma_f32_16x16x32_bf16 v[54:57], v[166:169], v[206:209], v[54:57]
	v_mfma_f32_16x16x32_bf16 v[46:49], v[174:177], v[206:209], v[46:49]
	v_mfma_f32_16x16x32_bf16 v[38:41], v[166:169], v[236:239], v[38:41]
	v_mfma_f32_16x16x32_bf16 v[30:33], v[174:177], v[236:239], v[30:33]
	v_mfma_f32_16x16x32_bf16 v[22:25], v[166:169], v[244:247], v[22:25]
	v_mfma_f32_16x16x32_bf16 v[14:17], v[174:177], v[244:247], v[14:17]
	v_mfma_f32_16x16x32_bf16 v[50:53], v[178:181], v[194:197], v[50:53]
	v_mfma_f32_16x16x32_bf16 v[42:45], v[186:189], v[194:197], v[42:45]
	v_mfma_f32_16x16x32_bf16 v[34:37], v[178:181], v[202:205], v[34:37]
	v_mfma_f32_16x16x32_bf16 v[26:29], v[186:189], v[202:205], v[26:29]
	v_mfma_f32_16x16x32_bf16 v[18:21], v[178:181], v[232:235], v[18:21]
	v_mfma_f32_16x16x32_bf16 v[10:13], v[186:189], v[232:235], v[10:13]
	v_mfma_f32_16x16x32_bf16 v[6:9], v[178:181], v[240:243], v[6:9]
	v_mfma_f32_16x16x32_bf16 v[2:5], v[186:189], v[240:243], v[2:5]
	v_mfma_f32_16x16x32_bf16 v[50:53], v[182:185], v[198:201], v[50:53]
	v_mfma_f32_16x16x32_bf16 v[42:45], v[190:193], v[198:201], v[42:45]
	v_mfma_f32_16x16x32_bf16 v[34:37], v[182:185], v[206:209], v[34:37]
	v_mfma_f32_16x16x32_bf16 v[26:29], v[190:193], v[206:209], v[26:29]
	v_mfma_f32_16x16x32_bf16 v[18:21], v[182:185], v[236:239], v[18:21]
	v_mfma_f32_16x16x32_bf16 v[10:13], v[190:193], v[236:239], v[10:13]
	v_mfma_f32_16x16x32_bf16 v[6:9], v[182:185], v[244:247], v[6:9]
	v_mfma_f32_16x16x32_bf16 v[2:5], v[190:193], v[244:247], v[2:5]
	s_setprio 0
	s_barrier
	s_add_i32 s53, 0, 0x18000
	v_add_u32_e32 v146, s53, v141
	s_add_i32 s54, 0, 0x1c000
	ds_read_b128 v[162:165], v146
	ds_read_b128 v[166:169], v146 offset:1024
	ds_read_b128 v[170:173], v146 offset:2048
	ds_read_b128 v[174:177], v146 offset:3072
	v_add_u32_e32 v146, s54, v141
	ds_read_b128 v[178:181], v146
	ds_read_b128 v[182:185], v146 offset:1024
	ds_read_b128 v[186:189], v146 offset:2048
	ds_read_b128 v[190:193], v146 offset:3072
	s_add_u32 s16, s22, 0x18000
	s_addc_u32 s17, s23, 0
	s_mov_b32 m0, s36
	v_lshl_add_u64 v[248:249], s[16:17], 0, v[134:135]
	ds_read_b128 v[194:197], v143 offset:32768
	ds_read_b128 v[198:201], v143 offset:33792
	ds_read_b128 v[202:205], v143 offset:34816
	ds_read_b128 v[206:209], v143 offset:35840
	ds_read_b128 v[232:235], v143 offset:36864
	ds_read_b128 v[236:239], v143 offset:37888
	ds_read_b128 v[240:243], v143 offset:38912
	ds_read_b128 v[244:247], v143 offset:39936
	global_load_lds_dwordx4 v[248:249], off
	v_lshl_add_u64 v[248:249], s[16:17], 0, v[132:133]
	s_mov_b32 m0, s37
	s_nop 0
	global_load_lds_dwordx4 v[248:249], off
	s_waitcnt vmcnt(8) lgkmcnt(0)
	s_barrier
	s_setprio 1
	v_mfma_f32_16x16x32_bf16 v[126:129], v[162:165], v[194:197], v[126:129]
	v_mfma_f32_16x16x32_bf16 v[122:125], v[170:173], v[194:197], v[122:125]
	v_mfma_f32_16x16x32_bf16 v[118:121], v[162:165], v[202:205], v[118:121]
	v_mfma_f32_16x16x32_bf16 v[110:113], v[170:173], v[202:205], v[110:113]
	v_mfma_f32_16x16x32_bf16 v[102:105], v[162:165], v[232:235], v[102:105]
	v_mfma_f32_16x16x32_bf16 v[94:97], v[170:173], v[232:235], v[94:97]
	v_mfma_f32_16x16x32_bf16 v[86:89], v[162:165], v[240:243], v[86:89]
	v_mfma_f32_16x16x32_bf16 v[78:81], v[170:173], v[240:243], v[78:81]
	v_mfma_f32_16x16x32_bf16 v[126:129], v[166:169], v[198:201], v[126:129]
	v_mfma_f32_16x16x32_bf16 v[122:125], v[174:177], v[198:201], v[122:125]
	v_mfma_f32_16x16x32_bf16 v[118:121], v[166:169], v[206:209], v[118:121]
	v_mfma_f32_16x16x32_bf16 v[110:113], v[174:177], v[206:209], v[110:113]
	v_mfma_f32_16x16x32_bf16 v[102:105], v[166:169], v[236:239], v[102:105]
	v_mfma_f32_16x16x32_bf16 v[94:97], v[174:177], v[236:239], v[94:97]
	v_mfma_f32_16x16x32_bf16 v[86:89], v[166:169], v[244:247], v[86:89]
	v_mfma_f32_16x16x32_bf16 v[78:81], v[174:177], v[244:247], v[78:81]
	v_mfma_f32_16x16x32_bf16 v[114:117], v[178:181], v[194:197], v[114:117]
	v_mfma_f32_16x16x32_bf16 v[106:109], v[186:189], v[194:197], v[106:109]
	v_mfma_f32_16x16x32_bf16 v[98:101], v[178:181], v[202:205], v[98:101]
	v_mfma_f32_16x16x32_bf16 v[90:93], v[186:189], v[202:205], v[90:93]
	v_mfma_f32_16x16x32_bf16 v[82:85], v[178:181], v[232:235], v[82:85]
	v_mfma_f32_16x16x32_bf16 v[74:77], v[186:189], v[232:235], v[74:77]
	v_mfma_f32_16x16x32_bf16 v[70:73], v[178:181], v[240:243], v[70:73]
	v_mfma_f32_16x16x32_bf16 v[66:69], v[186:189], v[240:243], v[66:69]
	v_mfma_f32_16x16x32_bf16 v[114:117], v[182:185], v[198:201], v[114:117]
	v_mfma_f32_16x16x32_bf16 v[106:109], v[190:193], v[198:201], v[106:109]
	v_mfma_f32_16x16x32_bf16 v[98:101], v[182:185], v[206:209], v[98:101]
	v_mfma_f32_16x16x32_bf16 v[90:93], v[190:193], v[206:209], v[90:93]
	v_mfma_f32_16x16x32_bf16 v[82:85], v[182:185], v[236:239], v[82:85]
	v_mfma_f32_16x16x32_bf16 v[74:77], v[190:193], v[236:239], v[74:77]
	v_mfma_f32_16x16x32_bf16 v[70:73], v[182:185], v[244:247], v[70:73]
	v_mfma_f32_16x16x32_bf16 v[66:69], v[190:193], v[244:247], v[66:69]
	s_setprio 0
	s_barrier
	s_add_i32 s16, s53, s30
	v_lshl_add_u64 v[144:145], v[144:145], 0, s[90:91]
	s_mov_b32 m0, s16
	ds_read_b128 v[194:197], v143 offset:49152
	ds_read_b128 v[198:201], v143 offset:50176
	ds_read_b128 v[202:205], v143 offset:51200
	ds_read_b128 v[206:209], v143 offset:52224
	ds_read_b128 v[232:235], v143 offset:53248
	ds_read_b128 v[236:239], v143 offset:54272
	ds_read_b128 v[240:243], v143 offset:55296
	ds_read_b128 v[244:247], v143 offset:56320
	global_load_lds_dwordx4 v[144:145], off
	s_add_i32 m0, s16, 0x2000
	s_add_u32 s16, s20, 0x18080
	v_lshl_add_u64 v[144:145], v[210:211], 0, s[90:91]
	s_addc_u32 s17, s21, 0
	s_add_i32 s20, s54, s30
	global_load_lds_dwordx4 v[144:145], off
	v_lshl_add_u64 v[144:145], s[16:17], 0, v[0:1]
	s_mov_b32 m0, s20
	s_nop 0
	global_load_lds_dwordx4 v[144:145], off
	v_lshl_add_u64 v[144:145], s[16:17], 0, v[130:131]
	s_add_i32 m0, s20, 0x2000
	s_nop 0
	global_load_lds_dwordx4 v[144:145], off
	v_lshl_add_u64 v[144:145], v[220:221], 0, s[90:91]
	s_mov_b32 m0, s38
	s_nop 0
	global_load_lds_dwordx4 v[144:145], off
	v_lshl_add_u64 v[144:145], v[222:223], 0, s[90:91]
	s_mov_b32 m0, s39
	s_nop 0
	global_load_lds_dwordx4 v[144:145], off
	s_waitcnt vmcnt(8) lgkmcnt(0)
	s_barrier
	s_setprio 1
	v_mfma_f32_16x16x32_bf16 v[62:65], v[162:165], v[194:197], v[62:65]
	v_mfma_f32_16x16x32_bf16 v[58:61], v[170:173], v[194:197], v[58:61]
	v_mfma_f32_16x16x32_bf16 v[54:57], v[162:165], v[202:205], v[54:57]
	v_mfma_f32_16x16x32_bf16 v[46:49], v[170:173], v[202:205], v[46:49]
	v_mfma_f32_16x16x32_bf16 v[38:41], v[162:165], v[232:235], v[38:41]
	v_mfma_f32_16x16x32_bf16 v[30:33], v[170:173], v[232:235], v[30:33]
	v_mfma_f32_16x16x32_bf16 v[22:25], v[162:165], v[240:243], v[22:25]
	v_mfma_f32_16x16x32_bf16 v[14:17], v[170:173], v[240:243], v[14:17]
	v_mfma_f32_16x16x32_bf16 v[62:65], v[166:169], v[198:201], v[62:65]
	v_mfma_f32_16x16x32_bf16 v[58:61], v[174:177], v[198:201], v[58:61]
	v_mfma_f32_16x16x32_bf16 v[54:57], v[166:169], v[206:209], v[54:57]
	v_mfma_f32_16x16x32_bf16 v[46:49], v[174:177], v[206:209], v[46:49]
	v_mfma_f32_16x16x32_bf16 v[38:41], v[166:169], v[236:239], v[38:41]
	v_mfma_f32_16x16x32_bf16 v[30:33], v[174:177], v[236:239], v[30:33]
	v_mfma_f32_16x16x32_bf16 v[22:25], v[166:169], v[244:247], v[22:25]
	v_mfma_f32_16x16x32_bf16 v[14:17], v[174:177], v[244:247], v[14:17]
	v_mfma_f32_16x16x32_bf16 v[50:53], v[178:181], v[194:197], v[50:53]
	v_mfma_f32_16x16x32_bf16 v[42:45], v[186:189], v[194:197], v[42:45]
	v_mfma_f32_16x16x32_bf16 v[34:37], v[178:181], v[202:205], v[34:37]
	v_mfma_f32_16x16x32_bf16 v[26:29], v[186:189], v[202:205], v[26:29]
	v_mfma_f32_16x16x32_bf16 v[18:21], v[178:181], v[232:235], v[18:21]
	v_mfma_f32_16x16x32_bf16 v[10:13], v[186:189], v[232:235], v[10:13]
	v_mfma_f32_16x16x32_bf16 v[6:9], v[178:181], v[240:243], v[6:9]
	v_mfma_f32_16x16x32_bf16 v[2:5], v[186:189], v[240:243], v[2:5]
	v_mfma_f32_16x16x32_bf16 v[50:53], v[182:185], v[198:201], v[50:53]
	v_mfma_f32_16x16x32_bf16 v[42:45], v[190:193], v[198:201], v[42:45]
	v_mfma_f32_16x16x32_bf16 v[34:37], v[182:185], v[206:209], v[34:37]
	v_mfma_f32_16x16x32_bf16 v[26:29], v[190:193], v[206:209], v[26:29]
	v_mfma_f32_16x16x32_bf16 v[18:21], v[182:185], v[236:239], v[18:21]
	v_mfma_f32_16x16x32_bf16 v[10:13], v[190:193], v[236:239], v[10:13]
	v_mfma_f32_16x16x32_bf16 v[6:9], v[182:185], v[244:247], v[6:9]
	v_mfma_f32_16x16x32_bf16 v[2:5], v[190:193], v[244:247], v[2:5]
	s_setprio 0
	s_barrier
	s_add_i32 s52, s52, 2
	s_add_u32 s46, s46, 0x100
	s_addc_u32 s47, s47, 0
	s_cmp_gt_u32 s52, 3
	s_mov_b64 s[16:17], s[18:19]
	s_cbranch_scc0 .LBB0_546
	s_and_b64 vcc, exec, s[12:13]
	s_cbranch_vccz .LBB0_549
	s_barrier

.LBB0_570:
	s_add_u32 s31, s24, s30
	s_addc_u32 s38, s25, 0
	s_add_u32 s36, s31, 0x100
	s_addc_u32 s37, s38, 0
	s_and_b64 s[34:35], s[28:29], exec
	s_cselect_b32 s35, s15, s37
	s_cselect_b32 s34, s76, s36
	s_add_u32 s30, s22, s30
	s_addc_u32 s36, s23, 0
	s_add_u32 s30, s30, 0x100
	s_addc_u32 s36, s36, 0
	s_add_i32 s56, 0, 0x10000
	s_and_b64 s[28:29], s[28:29], exec
	s_cselect_b32 s37, s13, s36
	s_cselect_b32 s36, s77, s30
	s_add_i32 s29, 0, 0x14000
	s_add_u32 s40, s31, 0x10080
	s_addc_u32 s41, s38, 0
	s_add_i32 vcc_lo, s56, s53
	s_add_i32 m0, s19, 0xc000
	s_add_i32 s57, s19, 0xe000
	s_add_i32 s82, vcc_lo, 0x2000
	v_add_u32_e32 v136, s56, v139
	s_add_u32 s38, s36, 0x10000
	ds_read_b128 v[142:145], v136
	ds_read_b128 v[162:165], v136 offset:1024
	ds_read_b128 v[166:169], v136 offset:2048
	ds_read_b128 v[170:173], v136 offset:3072
	v_add_u32_e32 v136, s29, v139
	s_addc_u32 s39, s37, 0
	s_add_i32 s96, s29, s53
	ds_read_b128 v[174:177], v136
	ds_read_b128 v[178:181], v136 offset:1024
	ds_read_b128 v[182:185], v136 offset:2048
	ds_read_b128 v[186:189], v136 offset:3072
	s_add_i32 s83, s96, 0x2000
	s_add_i32 s81, 0, 0x18000
	s_add_i32 s80, 0, 0x1c000
	s_add_u32 s30, s34, 0x10000
	s_addc_u32 s31, s35, 0
	s_add_i32 s79, s81, s53
	s_add_i32 s78, s79, 0x2000
	s_add_u32 s28, s36, 0x10080
	s_addc_u32 s29, s37, 0
	s_add_i32 vcc_hi, s80, s53
	s_add_i32 s56, vcc_hi, 0x2000
	v_lshl_add_u64 v[136:137], s[40:41], 0, v[130:131]
	ds_read_b128 v[190:193], v141
	ds_read_b128 v[194:197], v141 offset:1024
	ds_read_b128 v[198:201], v141 offset:2048
	ds_read_b128 v[202:205], v141 offset:3072
	ds_read_b128 v[206:209], v141 offset:4096
	ds_read_b128 v[232:235], v141 offset:5120
	ds_read_b128 v[236:239], v141 offset:6144
	ds_read_b128 v[240:243], v141 offset:7168
	global_load_lds_dwordx4 v[136:137], off
	v_lshl_add_u64 v[136:137], s[40:41], 0, v[132:133]
	s_mov_b32 m0, s57
	s_nop 0
	global_load_lds_dwordx4 v[136:137], off
	s_waitcnt vmcnt(8) lgkmcnt(0)
	s_barrier
	s_setprio 1
	v_mfma_f32_16x16x32_bf16 v[126:129], v[142:145], v[190:193], v[126:129]
	v_mfma_f32_16x16x32_bf16 v[122:125], v[166:169], v[190:193], v[122:125]
	v_mfma_f32_16x16x32_bf16 v[118:121], v[142:145], v[198:201], v[118:121]
	v_mfma_f32_16x16x32_bf16 v[110:113], v[166:169], v[198:201], v[110:113]
	v_mfma_f32_16x16x32_bf16 v[102:105], v[142:145], v[206:209], v[102:105]
	v_mfma_f32_16x16x32_bf16 v[94:97], v[166:169], v[206:209], v[94:97]
	v_mfma_f32_16x16x32_bf16 v[86:89], v[142:145], v[236:239], v[86:89]
	v_mfma_f32_16x16x32_bf16 v[78:81], v[166:169], v[236:239], v[78:81]
	v_mfma_f32_16x16x32_bf16 v[126:129], v[162:165], v[194:197], v[126:129]
	v_mfma_f32_16x16x32_bf16 v[122:125], v[170:173], v[194:197], v[122:125]
	v_mfma_f32_16x16x32_bf16 v[118:121], v[162:165], v[202:205], v[118:121]
	v_mfma_f32_16x16x32_bf16 v[110:113], v[170:173], v[202:205], v[110:113]
	v_mfma_f32_16x16x32_bf16 v[102:105], v[162:165], v[232:235], v[102:105]
	v_mfma_f32_16x16x32_bf16 v[94:97], v[170:173], v[232:235], v[94:97]
	v_mfma_f32_16x16x32_bf16 v[86:89], v[162:165], v[240:243], v[86:89]
	v_mfma_f32_16x16x32_bf16 v[78:81], v[170:173], v[240:243], v[78:81]
	v_mfma_f32_16x16x32_bf16 v[114:117], v[174:177], v[190:193], v[114:117]
	v_mfma_f32_16x16x32_bf16 v[106:109], v[182:185], v[190:193], v[106:109]
	v_mfma_f32_16x16x32_bf16 v[98:101], v[174:177], v[198:201], v[98:101]
	v_mfma_f32_16x16x32_bf16 v[90:93], v[182:185], v[198:201], v[90:93]
	v_mfma_f32_16x16x32_bf16 v[82:85], v[174:177], v[206:209], v[82:85]
	v_mfma_f32_16x16x32_bf16 v[74:77], v[182:185], v[206:209], v[74:77]
	v_mfma_f32_16x16x32_bf16 v[70:73], v[174:177], v[236:239], v[70:73]
	v_mfma_f32_16x16x32_bf16 v[66:69], v[182:185], v[236:239], v[66:69]
	v_mfma_f32_16x16x32_bf16 v[114:117], v[178:181], v[194:197], v[114:117]
	v_mfma_f32_16x16x32_bf16 v[106:109], v[186:189], v[194:197], v[106:109]
	v_mfma_f32_16x16x32_bf16 v[98:101], v[178:181], v[202:205], v[98:101]
	v_mfma_f32_16x16x32_bf16 v[90:93], v[186:189], v[202:205], v[90:93]
	v_mfma_f32_16x16x32_bf16 v[82:85], v[178:181], v[232:235], v[82:85]
	v_mfma_f32_16x16x32_bf16 v[74:77], v[186:189], v[232:235], v[74:77]
	v_mfma_f32_16x16x32_bf16 v[70:73], v[178:181], v[240:243], v[70:73]
	v_mfma_f32_16x16x32_bf16 v[66:69], v[186:189], v[240:243], v[66:69]
	s_setprio 0
	s_barrier
	s_mov_b32 m0, vcc_lo
	v_lshl_add_u64 v[136:137], s[36:37], 0, v[0:1]
	ds_read_b128 v[190:193], v141 offset:16384
	ds_read_b128 v[194:197], v141 offset:17408
	ds_read_b128 v[198:201], v141 offset:18432
	ds_read_b128 v[202:205], v141 offset:19456
	ds_read_b128 v[206:209], v141 offset:20480
	ds_read_b128 v[232:235], v141 offset:21504
	ds_read_b128 v[236:239], v141 offset:22528
	ds_read_b128 v[240:243], v141 offset:23552
	global_load_lds_dwordx4 v[136:137], off
	v_lshl_add_u64 v[210:211], s[36:37], 0, v[134:135]
	s_mov_b32 m0, s82
	v_lshl_add_u64 v[220:221], s[38:39], 0, v[0:1]
	global_load_lds_dwordx4 v[210:211], off
	s_mov_b32 m0, s96
	v_lshl_add_u64 v[222:223], s[34:35], 0, v[132:133]
	global_load_lds_dwordx4 v[220:221], off
	v_lshl_add_u64 v[220:221], s[38:39], 0, v[134:135]
	s_mov_b32 m0, s83
	s_nop 0
	global_load_lds_dwordx4 v[220:221], off
	v_lshl_add_u64 v[220:221], s[34:35], 0, v[130:131]
	s_mov_b32 m0, s19
	s_nop 0
	global_load_lds_dwordx4 v[220:221], off
	s_mov_b32 m0, s54
	s_nop 0
	global_load_lds_dwordx4 v[222:223], off
	s_waitcnt vmcnt(8) lgkmcnt(0)
	s_barrier
	s_setprio 1
	v_mfma_f32_16x16x32_bf16 v[62:65], v[142:145], v[190:193], v[62:65]
	v_mfma_f32_16x16x32_bf16 v[58:61], v[166:169], v[190:193], v[58:61]
	v_mfma_f32_16x16x32_bf16 v[54:57], v[142:145], v[198:201], v[54:57]
	v_mfma_f32_16x16x32_bf16 v[46:49], v[166:169], v[198:201], v[46:49]
	v_mfma_f32_16x16x32_bf16 v[38:41], v[142:145], v[206:209], v[38:41]
	v_mfma_f32_16x16x32_bf16 v[30:33], v[166:169], v[206:209], v[30:33]
	v_mfma_f32_16x16x32_bf16 v[22:25], v[142:145], v[236:239], v[22:25]
	v_mfma_f32_16x16x32_bf16 v[14:17], v[166:169], v[236:239], v[14:17]
	v_mfma_f32_16x16x32_bf16 v[62:65], v[162:165], v[194:197], v[62:65]
	v_mfma_f32_16x16x32_bf16 v[58:61], v[170:173], v[194:197], v[58:61]
	v_mfma_f32_16x16x32_bf16 v[54:57], v[162:165], v[202:205], v[54:57]
	v_mfma_f32_16x16x32_bf16 v[46:49], v[170:173], v[202:205], v[46:49]
	v_mfma_f32_16x16x32_bf16 v[38:41], v[162:165], v[232:235], v[38:41]
	v_mfma_f32_16x16x32_bf16 v[30:33], v[170:173], v[232:235], v[30:33]
	v_mfma_f32_16x16x32_bf16 v[22:25], v[162:165], v[240:243], v[22:25]
	v_mfma_f32_16x16x32_bf16 v[14:17], v[170:173], v[240:243], v[14:17]
	v_mfma_f32_16x16x32_bf16 v[50:53], v[174:177], v[190:193], v[50:53]
	v_mfma_f32_16x16x32_bf16 v[42:45], v[182:185], v[190:193], v[42:45]
	v_mfma_f32_16x16x32_bf16 v[34:37], v[174:177], v[198:201], v[34:37]
	v_mfma_f32_16x16x32_bf16 v[26:29], v[182:185], v[198:201], v[26:29]
	v_mfma_f32_16x16x32_bf16 v[18:21], v[174:177], v[206:209], v[18:21]
	v_mfma_f32_16x16x32_bf16 v[10:13], v[182:185], v[206:209], v[10:13]
	v_mfma_f32_16x16x32_bf16 v[6:9], v[174:177], v[236:239], v[6:9]
	v_mfma_f32_16x16x32_bf16 v[2:5], v[182:185], v[236:239], v[2:5]
	v_mfma_f32_16x16x32_bf16 v[50:53], v[178:181], v[194:197], v[50:53]
	v_mfma_f32_16x16x32_bf16 v[42:45], v[186:189], v[194:197], v[42:45]
	v_mfma_f32_16x16x32_bf16 v[34:37], v[178:181], v[202:205], v[34:37]
	v_mfma_f32_16x16x32_bf16 v[26:29], v[186:189], v[202:205], v[26:29]
	v_mfma_f32_16x16x32_bf16 v[18:21], v[178:181], v[232:235], v[18:21]
	v_mfma_f32_16x16x32_bf16 v[10:13], v[186:189], v[232:235], v[10:13]
	v_mfma_f32_16x16x32_bf16 v[6:9], v[178:181], v[240:243], v[6:9]
	v_mfma_f32_16x16x32_bf16 v[2:5], v[186:189], v[240:243], v[2:5]
	s_setprio 0
	s_barrier
	v_add_u32_e32 v146, s81, v139
	ds_read_b128 v[142:145], v146
	ds_read_b128 v[162:165], v146 offset:1024
	ds_read_b128 v[166:169], v146 offset:2048
	ds_read_b128 v[170:173], v146 offset:3072
	v_add_u32_e32 v146, s80, v139
	ds_read_b128 v[174:177], v146
	ds_read_b128 v[178:181], v146 offset:1024
	ds_read_b128 v[182:185], v146 offset:2048
	ds_read_b128 v[186:189], v146 offset:3072
	s_mov_b32 m0, s55
	v_lshl_add_u64 v[244:245], s[30:31], 0, v[130:131]
	ds_read_b128 v[190:193], v141 offset:32768
	ds_read_b128 v[194:197], v141 offset:33792
	ds_read_b128 v[198:201], v141 offset:34816
	ds_read_b128 v[202:205], v141 offset:35840
	ds_read_b128 v[206:209], v141 offset:36864
	ds_read_b128 v[232:235], v141 offset:37888
	ds_read_b128 v[236:239], v141 offset:38912
	ds_read_b128 v[240:243], v141 offset:39936
	global_load_lds_dwordx4 v[244:245], off
	v_lshl_add_u64 v[244:245], s[30:31], 0, v[132:133]
	s_mov_b32 m0, s70
	s_nop 0
	global_load_lds_dwordx4 v[244:245], off
	s_waitcnt vmcnt(8) lgkmcnt(0)
	s_barrier
	s_setprio 1
	v_mfma_f32_16x16x32_bf16 v[126:129], v[142:145], v[190:193], v[126:129]
	v_mfma_f32_16x16x32_bf16 v[122:125], v[166:169], v[190:193], v[122:125]
	v_mfma_f32_16x16x32_bf16 v[118:121], v[142:145], v[198:201], v[118:121]
	v_mfma_f32_16x16x32_bf16 v[110:113], v[166:169], v[198:201], v[110:113]
	v_mfma_f32_16x16x32_bf16 v[102:105], v[142:145], v[206:209], v[102:105]
	v_mfma_f32_16x16x32_bf16 v[94:97], v[166:169], v[206:209], v[94:97]
	v_mfma_f32_16x16x32_bf16 v[86:89], v[142:145], v[236:239], v[86:89]
	v_mfma_f32_16x16x32_bf16 v[78:81], v[166:169], v[236:239], v[78:81]
	v_mfma_f32_16x16x32_bf16 v[126:129], v[162:165], v[194:197], v[126:129]
	v_mfma_f32_16x16x32_bf16 v[122:125], v[170:173], v[194:197], v[122:125]
	v_mfma_f32_16x16x32_bf16 v[118:121], v[162:165], v[202:205], v[118:121]
	v_mfma_f32_16x16x32_bf16 v[110:113], v[170:173], v[202:205], v[110:113]
	v_mfma_f32_16x16x32_bf16 v[102:105], v[162:165], v[232:235], v[102:105]
	v_mfma_f32_16x16x32_bf16 v[94:97], v[170:173], v[232:235], v[94:97]
	v_mfma_f32_16x16x32_bf16 v[86:89], v[162:165], v[240:243], v[86:89]
	v_mfma_f32_16x16x32_bf16 v[78:81], v[170:173], v[240:243], v[78:81]
	v_mfma_f32_16x16x32_bf16 v[114:117], v[174:177], v[190:193], v[114:117]
	v_mfma_f32_16x16x32_bf16 v[106:109], v[182:185], v[190:193], v[106:109]
	v_mfma_f32_16x16x32_bf16 v[98:101], v[174:177], v[198:201], v[98:101]
	v_mfma_f32_16x16x32_bf16 v[90:93], v[182:185], v[198:201], v[90:93]
	v_mfma_f32_16x16x32_bf16 v[82:85], v[174:177], v[206:209], v[82:85]
	v_mfma_f32_16x16x32_bf16 v[74:77], v[182:185], v[206:209], v[74:77]
	v_mfma_f32_16x16x32_bf16 v[70:73], v[174:177], v[236:239], v[70:73]
	v_mfma_f32_16x16x32_bf16 v[66:69], v[182:185], v[236:239], v[66:69]
	v_mfma_f32_16x16x32_bf16 v[114:117], v[178:181], v[194:197], v[114:117]
	v_mfma_f32_16x16x32_bf16 v[106:109], v[186:189], v[194:197], v[106:109]
	v_mfma_f32_16x16x32_bf16 v[98:101], v[178:181], v[202:205], v[98:101]
	v_mfma_f32_16x16x32_bf16 v[90:93], v[186:189], v[202:205], v[90:93]
	v_mfma_f32_16x16x32_bf16 v[82:85], v[178:181], v[232:235], v[82:85]
	v_mfma_f32_16x16x32_bf16 v[74:77], v[186:189], v[232:235], v[74:77]
	v_mfma_f32_16x16x32_bf16 v[70:73], v[178:181], v[240:243], v[70:73]
	v_mfma_f32_16x16x32_bf16 v[66:69], v[186:189], v[240:243], v[66:69]
	s_setprio 0
	s_barrier
	s_mov_b32 m0, s79
	v_lshl_add_u64 v[136:137], v[136:137], 0, s[90:91]
	ds_read_b128 v[190:193], v141 offset:49152
	ds_read_b128 v[194:197], v141 offset:50176
	ds_read_b128 v[198:201], v141 offset:51200
	ds_read_b128 v[202:205], v141 offset:52224
	ds_read_b128 v[206:209], v141 offset:53248
	ds_read_b128 v[232:235], v141 offset:54272
	ds_read_b128 v[236:239], v141 offset:55296
	ds_read_b128 v[240:243], v141 offset:56320
	global_load_lds_dwordx4 v[136:137], off
	v_lshl_add_u64 v[136:137], v[210:211], 0, s[90:91]
	s_mov_b32 m0, s78
	s_nop 0
	global_load_lds_dwordx4 v[136:137], off
	v_lshl_add_u64 v[136:137], s[28:29], 0, v[0:1]
	s_mov_b32 m0, vcc_hi
	s_nop 0
	global_load_lds_dwordx4 v[136:137], off
	v_lshl_add_u64 v[136:137], s[28:29], 0, v[134:135]
	s_mov_b32 m0, s56
	s_nop 0
	global_load_lds_dwordx4 v[136:137], off
	v_lshl_add_u64 v[136:137], v[220:221], 0, s[90:91]
	s_mov_b32 m0, s71
	s_nop 0
	global_load_lds_dwordx4 v[136:137], off
	v_lshl_add_u64 v[136:137], v[222:223], 0, s[90:91]
	s_mov_b32 m0, s72
	s_nop 0
	global_load_lds_dwordx4 v[136:137], off
	s_waitcnt vmcnt(8) lgkmcnt(0)
	s_barrier
	s_setprio 1
	v_mfma_f32_16x16x32_bf16 v[62:65], v[142:145], v[190:193], v[62:65]
	v_mfma_f32_16x16x32_bf16 v[58:61], v[166:169], v[190:193], v[58:61]
	v_mfma_f32_16x16x32_bf16 v[54:57], v[142:145], v[198:201], v[54:57]
	v_mfma_f32_16x16x32_bf16 v[46:49], v[166:169], v[198:201], v[46:49]
	v_mfma_f32_16x16x32_bf16 v[38:41], v[142:145], v[206:209], v[38:41]
	v_mfma_f32_16x16x32_bf16 v[30:33], v[166:169], v[206:209], v[30:33]
	v_mfma_f32_16x16x32_bf16 v[22:25], v[142:145], v[236:239], v[22:25]
	v_mfma_f32_16x16x32_bf16 v[14:17], v[166:169], v[236:239], v[14:17]
	v_mfma_f32_16x16x32_bf16 v[62:65], v[162:165], v[194:197], v[62:65]
	v_mfma_f32_16x16x32_bf16 v[58:61], v[170:173], v[194:197], v[58:61]
	v_mfma_f32_16x16x32_bf16 v[54:57], v[162:165], v[202:205], v[54:57]
	v_mfma_f32_16x16x32_bf16 v[46:49], v[170:173], v[202:205], v[46:49]
	v_mfma_f32_16x16x32_bf16 v[38:41], v[162:165], v[232:235], v[38:41]
	v_mfma_f32_16x16x32_bf16 v[30:33], v[170:173], v[232:235], v[30:33]
	v_mfma_f32_16x16x32_bf16 v[22:25], v[162:165], v[240:243], v[22:25]
	v_mfma_f32_16x16x32_bf16 v[14:17], v[170:173], v[240:243], v[14:17]
	v_mfma_f32_16x16x32_bf16 v[50:53], v[174:177], v[190:193], v[50:53]
	v_mfma_f32_16x16x32_bf16 v[42:45], v[182:185], v[190:193], v[42:45]
	v_mfma_f32_16x16x32_bf16 v[34:37], v[174:177], v[198:201], v[34:37]
	v_mfma_f32_16x16x32_bf16 v[26:29], v[182:185], v[198:201], v[26:29]
	v_mfma_f32_16x16x32_bf16 v[18:21], v[174:177], v[206:209], v[18:21]
	v_mfma_f32_16x16x32_bf16 v[10:13], v[182:185], v[206:209], v[10:13]
	v_mfma_f32_16x16x32_bf16 v[6:9], v[174:177], v[236:239], v[6:9]
	v_mfma_f32_16x16x32_bf16 v[2:5], v[182:185], v[236:239], v[2:5]
	v_mfma_f32_16x16x32_bf16 v[50:53], v[178:181], v[194:197], v[50:53]
	v_mfma_f32_16x16x32_bf16 v[42:45], v[186:189], v[194:197], v[42:45]
	v_mfma_f32_16x16x32_bf16 v[34:37], v[178:181], v[202:205], v[34:37]
	v_mfma_f32_16x16x32_bf16 v[26:29], v[186:189], v[202:205], v[26:29]
	v_mfma_f32_16x16x32_bf16 v[18:21], v[178:181], v[232:235], v[18:21]
	v_mfma_f32_16x16x32_bf16 v[10:13], v[186:189], v[232:235], v[10:13]
	v_mfma_f32_16x16x32_bf16 v[6:9], v[178:181], v[240:243], v[6:9]
	v_mfma_f32_16x16x32_bf16 v[2:5], v[186:189], v[240:243], v[2:5]
	s_setprio 0
	s_barrier
	s_movk_i32 s30, 0x100
	s_andn2_b64 vcc, exec, s[26:27]
	s_mov_b64 s[28:29], -1
	s_mov_b64 s[26:27], 0
	s_cbranch_vccz .LBB0_570
	s_and_b64 vcc, exec, s[10:11]
	s_cbranch_vccz .LBB0_573
	s_barrier

.LBB0_586:
	s_ashr_i32 s13, s12, 31
	s_lshl_b64 s[16:17], s[12:13], 17
	s_add_u32 s16, s30, s16
	v_cmp_lt_i64_e32 vcc, s[6:7], v[152:153]
	s_addc_u32 s17, s31, s17
	s_and_b64 s[18:19], vcc, exec
	s_cselect_b32 s27, s17, s21
	s_cselect_b32 s26, s16, s20
	s_ashr_i32 s11, s10, 31
	s_lshl_b64 s[18:19], s[10:11], 17
	s_add_u32 s18, s34, s18
	s_addc_u32 s19, s35, s19
	s_and_b64 s[24:25], vcc, exec
	s_cselect_b32 s25, s19, s23
	s_cselect_b32 s24, s18, s22
	s_add_i32 s13, 0, 0x10000
	s_add_i32 s45, 0, 0x14000
	v_add_u32_e32 v146, s13, v43
	v_add_u32_e32 v160, s45, v43
	ds_read_b128 v[2:5], v146
	ds_read_b128 v[6:9], v146 offset:1024
	ds_read_b128 v[10:13], v146 offset:2048
	ds_read_b128 v[14:17], v146 offset:3072
	ds_read_b128 v[18:21], v160
	ds_read_b128 v[22:25], v160 offset:1024
	ds_read_b128 v[26:29], v160 offset:2048
	ds_read_b128 v[30:33], v160 offset:3072
	s_add_u32 s46, s20, 0x10080
	s_addc_u32 s47, s21, 0
	s_add_i32 s53, s15, 0xc000
	v_lshl_add_u64 v[40:41], s[46:47], 0, v[34:35]
	s_mov_b32 m0, s53
	s_add_i32 s11, s15, 0xe000
	ds_read_b128 v[46:49], v45
	ds_read_b128 v[50:53], v45 offset:1024
	ds_read_b128 v[54:57], v45 offset:2048
	ds_read_b128 v[58:61], v45 offset:3072
	ds_read_b128 v[62:65], v45 offset:4096
	ds_read_b128 v[66:69], v45 offset:5120
	ds_read_b128 v[70:73], v45 offset:6144
	ds_read_b128 v[74:77], v45 offset:7168
	global_load_lds_dwordx4 v[40:41], off
	v_lshl_add_u64 v[40:41], s[46:47], 0, v[36:37]
	s_mov_b32 m0, s11
	s_nop 0
	global_load_lds_dwordx4 v[40:41], off
	s_waitcnt vmcnt(8) lgkmcnt(0)
	s_barrier
	s_setprio 1
	v_mfma_f32_16x16x32_bf16 v[78:81], v[2:5], v[46:49], 0
	v_mfma_f32_16x16x32_bf16 v[82:85], v[10:13], v[46:49], 0
	v_mfma_f32_16x16x32_bf16 v[86:89], v[2:5], v[54:57], 0
	v_mfma_f32_16x16x32_bf16 v[90:93], v[10:13], v[54:57], 0
	v_mfma_f32_16x16x32_bf16 v[94:97], v[2:5], v[62:65], 0
	v_mfma_f32_16x16x32_bf16 v[98:101], v[10:13], v[62:65], 0
	v_mfma_f32_16x16x32_bf16 v[102:105], v[2:5], v[70:73], 0
	v_mfma_f32_16x16x32_bf16 v[106:109], v[10:13], v[70:73], 0
	v_mfma_f32_16x16x32_bf16 v[78:81], v[6:9], v[50:53], v[78:81]
	v_mfma_f32_16x16x32_bf16 v[82:85], v[14:17], v[50:53], v[82:85]
	v_mfma_f32_16x16x32_bf16 v[86:89], v[6:9], v[58:61], v[86:89]
	v_mfma_f32_16x16x32_bf16 v[90:93], v[14:17], v[58:61], v[90:93]
	v_mfma_f32_16x16x32_bf16 v[94:97], v[6:9], v[66:69], v[94:97]
	v_mfma_f32_16x16x32_bf16 v[98:101], v[14:17], v[66:69], v[98:101]
	v_mfma_f32_16x16x32_bf16 v[102:105], v[6:9], v[74:77], v[102:105]
	v_mfma_f32_16x16x32_bf16 v[106:109], v[14:17], v[74:77], v[106:109]
	v_mfma_f32_16x16x32_bf16 v[110:113], v[18:21], v[46:49], 0
	v_mfma_f32_16x16x32_bf16 v[46:49], v[26:29], v[46:49], 0
	v_mfma_f32_16x16x32_bf16 v[110:113], v[22:25], v[50:53], v[110:113]
	v_mfma_f32_16x16x32_bf16 v[46:49], v[30:33], v[50:53], v[46:49]
	v_mfma_f32_16x16x32_bf16 v[50:53], v[18:21], v[54:57], 0
	v_mfma_f32_16x16x32_bf16 v[54:57], v[26:29], v[54:57], 0
	v_mfma_f32_16x16x32_bf16 v[50:53], v[22:25], v[58:61], v[50:53]
	v_mfma_f32_16x16x32_bf16 v[54:57], v[30:33], v[58:61], v[54:57]
	v_mfma_f32_16x16x32_bf16 v[58:61], v[18:21], v[62:65], 0
	v_mfma_f32_16x16x32_bf16 v[62:65], v[26:29], v[62:65], 0
	v_mfma_f32_16x16x32_bf16 v[58:61], v[22:25], v[66:69], v[58:61]
	v_mfma_f32_16x16x32_bf16 v[62:65], v[30:33], v[66:69], v[62:65]
	v_mfma_f32_16x16x32_bf16 v[66:69], v[18:21], v[70:73], 0
	v_mfma_f32_16x16x32_bf16 v[70:73], v[26:29], v[70:73], 0
	v_mfma_f32_16x16x32_bf16 v[66:69], v[22:25], v[74:77], v[66:69]
	v_mfma_f32_16x16x32_bf16 v[70:73], v[30:33], v[74:77], v[70:73]
	s_setprio 0
	s_barrier
	s_add_i32 s47, s13, s36
	v_lshl_add_u64 v[40:41], s[22:23], 0, v[0:1]
	s_mov_b64 s[56:57], 0x100
	s_add_i32 s13, s47, 0x2000
	v_lshl_add_u64 v[142:143], v[40:41], 0, s[56:57]
	s_mov_b32 m0, s47
	v_lshl_add_u64 v[210:211], s[22:23], 0, v[38:39]
	s_add_u32 s54, s22, 0x10100
	ds_read_b128 v[74:77], v45 offset:16384
	ds_read_b128 v[114:117], v45 offset:17408
	ds_read_b128 v[118:121], v45 offset:18432
	ds_read_b128 v[122:125], v45 offset:19456
	ds_read_b128 v[126:129], v45 offset:20480
	ds_read_b128 v[130:133], v45 offset:21504
	ds_read_b128 v[134:137], v45 offset:22528
	ds_read_b128 v[138:141], v45 offset:23552
	global_load_lds_dwordx4 v[142:143], off
	v_lshl_add_u64 v[142:143], v[210:211], 0, s[56:57]
	s_mov_b32 m0, s13
	s_addc_u32 s55, s23, 0
	s_add_i32 s45, s45, s36
	global_load_lds_dwordx4 v[142:143], off
	v_lshl_add_u64 v[142:143], s[54:55], 0, v[0:1]
	s_mov_b32 m0, s45
	s_add_i32 s46, s45, 0x2000
	global_load_lds_dwordx4 v[142:143], off
	v_lshl_add_u64 v[142:143], s[54:55], 0, v[38:39]
	s_mov_b32 m0, s46
	v_lshl_add_u64 v[220:221], s[20:21], 0, v[34:35]
	global_load_lds_dwordx4 v[142:143], off
	v_lshl_add_u64 v[142:143], v[220:221], 0, s[56:57]
	s_mov_b32 m0, s15
	v_lshl_add_u64 v[222:223], s[20:21], 0, v[36:37]
	global_load_lds_dwordx4 v[142:143], off
	v_lshl_add_u64 v[142:143], v[222:223], 0, s[56:57]
	s_mov_b32 m0, s37
	s_nop 0
	global_load_lds_dwordx4 v[142:143], off
	s_waitcnt vmcnt(8) lgkmcnt(0)
	s_barrier
	s_setprio 1
	v_mfma_f32_16x16x32_bf16 v[142:145], v[2:5], v[74:77], 0
	v_mfma_f32_16x16x32_bf16 v[166:169], v[2:5], v[118:121], 0
	v_mfma_f32_16x16x32_bf16 v[174:177], v[2:5], v[126:129], 0
	v_mfma_f32_16x16x32_bf16 v[2:5], v[2:5], v[134:137], 0
	v_mfma_f32_16x16x32_bf16 v[142:145], v[6:9], v[114:117], v[142:145]
	v_mfma_f32_16x16x32_bf16 v[162:165], v[10:13], v[74:77], 0
	v_mfma_f32_16x16x32_bf16 v[166:169], v[6:9], v[122:125], v[166:169]
	v_mfma_f32_16x16x32_bf16 v[170:173], v[10:13], v[118:121], 0
	v_mfma_f32_16x16x32_bf16 v[174:177], v[6:9], v[130:133], v[174:177]
	v_mfma_f32_16x16x32_bf16 v[178:181], v[10:13], v[126:129], 0
	v_mfma_f32_16x16x32_bf16 v[2:5], v[6:9], v[138:141], v[2:5]
	v_mfma_f32_16x16x32_bf16 v[6:9], v[10:13], v[134:137], 0
	v_mfma_f32_16x16x32_bf16 v[162:165], v[14:17], v[114:117], v[162:165]
	v_mfma_f32_16x16x32_bf16 v[170:173], v[14:17], v[122:125], v[170:173]
	v_mfma_f32_16x16x32_bf16 v[178:181], v[14:17], v[130:133], v[178:181]
	v_mfma_f32_16x16x32_bf16 v[6:9], v[14:17], v[138:141], v[6:9]
	v_mfma_f32_16x16x32_bf16 v[10:13], v[18:21], v[74:77], 0
	v_mfma_f32_16x16x32_bf16 v[14:17], v[26:29], v[74:77], 0
	v_mfma_f32_16x16x32_bf16 v[10:13], v[22:25], v[114:117], v[10:13]
	v_mfma_f32_16x16x32_bf16 v[14:17], v[30:33], v[114:117], v[14:17]
	v_mfma_f32_16x16x32_bf16 v[74:77], v[18:21], v[118:121], 0
	v_mfma_f32_16x16x32_bf16 v[114:117], v[26:29], v[118:121], 0
	v_mfma_f32_16x16x32_bf16 v[118:121], v[18:21], v[126:129], 0
	v_mfma_f32_16x16x32_bf16 v[18:21], v[18:21], v[134:137], 0
	v_mfma_f32_16x16x32_bf16 v[74:77], v[22:25], v[122:125], v[74:77]
	v_mfma_f32_16x16x32_bf16 v[114:117], v[30:33], v[122:125], v[114:117]
	v_mfma_f32_16x16x32_bf16 v[118:121], v[22:25], v[130:133], v[118:121]
	v_mfma_f32_16x16x32_bf16 v[122:125], v[26:29], v[126:129], 0
	v_mfma_f32_16x16x32_bf16 v[18:21], v[22:25], v[138:141], v[18:21]
	v_mfma_f32_16x16x32_bf16 v[22:25], v[26:29], v[134:137], 0
	v_mfma_f32_16x16x32_bf16 v[122:125], v[30:33], v[130:133], v[122:125]
	v_mfma_f32_16x16x32_bf16 v[22:25], v[30:33], v[138:141], v[22:25]
	s_setprio 0
	s_barrier
	s_add_i32 s52, 0, 0x18000
	s_add_i32 s70, 0, 0x1c000
	v_add_u32_e32 v231, s52, v43
	v_add_u32_e32 v246, s70, v43
	ds_read_b128 v[26:29], v231
	ds_read_b128 v[30:33], v231 offset:1024
	ds_read_b128 v[126:129], v231 offset:2048
	ds_read_b128 v[130:133], v231 offset:3072
	ds_read_b128 v[134:137], v246
	ds_read_b128 v[138:141], v246 offset:1024
	ds_read_b128 v[182:185], v246 offset:2048
	ds_read_b128 v[186:189], v246 offset:3072
	s_add_u32 s54, s20, 0x10100
	s_addc_u32 s55, s21, 0
	s_mov_b32 m0, s38
	v_lshl_add_u64 v[244:245], s[54:55], 0, v[34:35]
	ds_read_b128 v[190:193], v45 offset:32768
	ds_read_b128 v[194:197], v45 offset:33792
	ds_read_b128 v[198:201], v45 offset:34816
	ds_read_b128 v[202:205], v45 offset:35840
	ds_read_b128 v[206:209], v45 offset:36864
	ds_read_b128 v[232:235], v45 offset:37888
	ds_read_b128 v[236:239], v45 offset:38912
	ds_read_b128 v[240:243], v45 offset:39936
	global_load_lds_dwordx4 v[244:245], off
	v_lshl_add_u64 v[244:245], s[54:55], 0, v[36:37]
	s_mov_b32 m0, s39
	s_nop 0
	global_load_lds_dwordx4 v[244:245], off
	s_waitcnt vmcnt(8) lgkmcnt(0)
	s_barrier
	s_setprio 1
	v_mfma_f32_16x16x32_bf16 v[78:81], v[26:29], v[190:193], v[78:81]
	v_mfma_f32_16x16x32_bf16 v[82:85], v[126:129], v[190:193], v[82:85]
	v_mfma_f32_16x16x32_bf16 v[86:89], v[26:29], v[198:201], v[86:89]
	v_mfma_f32_16x16x32_bf16 v[90:93], v[126:129], v[198:201], v[90:93]
	v_mfma_f32_16x16x32_bf16 v[94:97], v[26:29], v[206:209], v[94:97]
	v_mfma_f32_16x16x32_bf16 v[98:101], v[126:129], v[206:209], v[98:101]
	v_mfma_f32_16x16x32_bf16 v[102:105], v[26:29], v[236:239], v[102:105]
	v_mfma_f32_16x16x32_bf16 v[106:109], v[126:129], v[236:239], v[106:109]
	v_mfma_f32_16x16x32_bf16 v[78:81], v[30:33], v[194:197], v[78:81]
	v_mfma_f32_16x16x32_bf16 v[82:85], v[130:133], v[194:197], v[82:85]
	v_mfma_f32_16x16x32_bf16 v[86:89], v[30:33], v[202:205], v[86:89]
	v_mfma_f32_16x16x32_bf16 v[90:93], v[130:133], v[202:205], v[90:93]
	v_mfma_f32_16x16x32_bf16 v[94:97], v[30:33], v[232:235], v[94:97]
	v_mfma_f32_16x16x32_bf16 v[98:101], v[130:133], v[232:235], v[98:101]
	v_mfma_f32_16x16x32_bf16 v[102:105], v[30:33], v[240:243], v[102:105]
	v_mfma_f32_16x16x32_bf16 v[106:109], v[130:133], v[240:243], v[106:109]
	v_mfma_f32_16x16x32_bf16 v[110:113], v[134:137], v[190:193], v[110:113]
	v_mfma_f32_16x16x32_bf16 v[46:49], v[182:185], v[190:193], v[46:49]
	v_mfma_f32_16x16x32_bf16 v[50:53], v[134:137], v[198:201], v[50:53]
	v_mfma_f32_16x16x32_bf16 v[54:57], v[182:185], v[198:201], v[54:57]
	v_mfma_f32_16x16x32_bf16 v[58:61], v[134:137], v[206:209], v[58:61]
	v_mfma_f32_16x16x32_bf16 v[62:65], v[182:185], v[206:209], v[62:65]
	v_mfma_f32_16x16x32_bf16 v[66:69], v[134:137], v[236:239], v[66:69]
	v_mfma_f32_16x16x32_bf16 v[70:73], v[182:185], v[236:239], v[70:73]
	v_mfma_f32_16x16x32_bf16 v[110:113], v[138:141], v[194:197], v[110:113]
	v_mfma_f32_16x16x32_bf16 v[46:49], v[186:189], v[194:197], v[46:49]
	v_mfma_f32_16x16x32_bf16 v[50:53], v[138:141], v[202:205], v[50:53]
	v_mfma_f32_16x16x32_bf16 v[54:57], v[186:189], v[202:205], v[54:57]
	v_mfma_f32_16x16x32_bf16 v[58:61], v[138:141], v[232:235], v[58:61]
	v_mfma_f32_16x16x32_bf16 v[62:65], v[186:189], v[232:235], v[62:65]
	v_mfma_f32_16x16x32_bf16 v[66:69], v[138:141], v[240:243], v[66:69]
	v_mfma_f32_16x16x32_bf16 v[70:73], v[186:189], v[240:243], v[70:73]
	s_setprio 0
	s_barrier
	s_add_i32 s54, s52, s36
	s_mov_b64 s[76:77], 0x180
	s_add_i32 s52, s54, 0x2000
	v_lshl_add_u64 v[40:41], v[40:41], 0, s[76:77]
	s_mov_b32 m0, s54
	s_add_u32 s56, s22, 0x10180
	ds_read_b128 v[190:193], v45 offset:49152
	ds_read_b128 v[194:197], v45 offset:50176
	ds_read_b128 v[198:201], v45 offset:51200
	ds_read_b128 v[202:205], v45 offset:52224
	ds_read_b128 v[206:209], v45 offset:53248
	ds_read_b128 v[232:235], v45 offset:54272
	ds_read_b128 v[236:239], v45 offset:55296
	ds_read_b128 v[240:243], v45 offset:56320
	global_load_lds_dwordx4 v[40:41], off
	v_lshl_add_u64 v[40:41], v[210:211], 0, s[76:77]
	s_mov_b32 m0, s52
	s_addc_u32 s57, s23, 0
	s_add_i32 s22, s70, s36
	global_load_lds_dwordx4 v[40:41], off
	v_lshl_add_u64 v[40:41], s[56:57], 0, v[0:1]
	s_mov_b32 m0, s22
	s_add_i32 s23, s22, 0x2000
	global_load_lds_dwordx4 v[40:41], off
	v_lshl_add_u64 v[40:41], s[56:57], 0, v[38:39]
	s_mov_b32 m0, s23
	s_nop 0
	global_load_lds_dwordx4 v[40:41], off
	v_lshl_add_u64 v[40:41], v[220:221], 0, s[76:77]
	s_mov_b32 m0, s40
	s_nop 0
	global_load_lds_dwordx4 v[40:41], off
	v_lshl_add_u64 v[40:41], v[222:223], 0, s[76:77]
	s_mov_b32 m0, s41
	s_nop 0
	global_load_lds_dwordx4 v[40:41], off
	s_waitcnt vmcnt(8) lgkmcnt(0)
	s_barrier
	s_setprio 1
	v_mfma_f32_16x16x32_bf16 v[142:145], v[26:29], v[190:193], v[142:145]
	v_mfma_f32_16x16x32_bf16 v[162:165], v[126:129], v[190:193], v[162:165]
	v_mfma_f32_16x16x32_bf16 v[166:169], v[26:29], v[198:201], v[166:169]
	v_mfma_f32_16x16x32_bf16 v[170:173], v[126:129], v[198:201], v[170:173]
	v_mfma_f32_16x16x32_bf16 v[174:177], v[26:29], v[206:209], v[174:177]
	v_mfma_f32_16x16x32_bf16 v[178:181], v[126:129], v[206:209], v[178:181]
	v_mfma_f32_16x16x32_bf16 v[2:5], v[26:29], v[236:239], v[2:5]
	v_mfma_f32_16x16x32_bf16 v[6:9], v[126:129], v[236:239], v[6:9]
	v_mfma_f32_16x16x32_bf16 v[142:145], v[30:33], v[194:197], v[142:145]
	v_mfma_f32_16x16x32_bf16 v[162:165], v[130:133], v[194:197], v[162:165]
	v_mfma_f32_16x16x32_bf16 v[166:169], v[30:33], v[202:205], v[166:169]
	v_mfma_f32_16x16x32_bf16 v[170:173], v[130:133], v[202:205], v[170:173]
	v_mfma_f32_16x16x32_bf16 v[174:177], v[30:33], v[232:235], v[174:177]
	v_mfma_f32_16x16x32_bf16 v[178:181], v[130:133], v[232:235], v[178:181]
	v_mfma_f32_16x16x32_bf16 v[2:5], v[30:33], v[240:243], v[2:5]
	v_mfma_f32_16x16x32_bf16 v[6:9], v[130:133], v[240:243], v[6:9]
	v_mfma_f32_16x16x32_bf16 v[10:13], v[134:137], v[190:193], v[10:13]
	v_mfma_f32_16x16x32_bf16 v[14:17], v[182:185], v[190:193], v[14:17]
	v_mfma_f32_16x16x32_bf16 v[26:29], v[134:137], v[198:201], v[74:77]
	v_mfma_f32_16x16x32_bf16 v[30:33], v[182:185], v[198:201], v[114:117]
	v_mfma_f32_16x16x32_bf16 v[74:77], v[134:137], v[206:209], v[118:121]
	v_mfma_f32_16x16x32_bf16 v[114:117], v[182:185], v[206:209], v[122:125]
	v_mfma_f32_16x16x32_bf16 v[18:21], v[134:137], v[236:239], v[18:21]
	v_mfma_f32_16x16x32_bf16 v[22:25], v[182:185], v[236:239], v[22:25]
	v_mfma_f32_16x16x32_bf16 v[10:13], v[138:141], v[194:197], v[10:13]
	v_mfma_f32_16x16x32_bf16 v[14:17], v[186:189], v[194:197], v[14:17]
	v_mfma_f32_16x16x32_bf16 v[26:29], v[138:141], v[202:205], v[26:29]
	v_mfma_f32_16x16x32_bf16 v[30:33], v[186:189], v[202:205], v[30:33]
	v_mfma_f32_16x16x32_bf16 v[74:77], v[138:141], v[232:235], v[74:77]
	v_mfma_f32_16x16x32_bf16 v[114:117], v[186:189], v[232:235], v[114:117]
	v_mfma_f32_16x16x32_bf16 v[18:21], v[138:141], v[240:243], v[18:21]
	v_mfma_f32_16x16x32_bf16 v[22:25], v[186:189], v[240:243], v[22:25]
	s_setprio 0
	s_barrier
	ds_read_b128 v[118:121], v146
	ds_read_b128 v[122:125], v146 offset:1024
	ds_read_b128 v[126:129], v146 offset:2048
	ds_read_b128 v[130:133], v146 offset:3072
	ds_read_b128 v[134:137], v160
	ds_read_b128 v[138:141], v160 offset:1024
	ds_read_b128 v[182:185], v160 offset:2048
	ds_read_b128 v[186:189], v160 offset:3072
	s_add_u32 s20, s20, 0x10180
	s_addc_u32 s21, s21, 0
	s_mov_b32 m0, s53
	v_lshl_add_u64 v[40:41], s[20:21], 0, v[34:35]
	ds_read_b128 v[190:193], v45
	ds_read_b128 v[194:197], v45 offset:1024
	ds_read_b128 v[198:201], v45 offset:2048
	ds_read_b128 v[202:205], v45 offset:3072
	ds_read_b128 v[206:209], v45 offset:4096
	ds_read_b128 v[232:235], v45 offset:5120
	ds_read_b128 v[236:239], v45 offset:6144
	ds_read_b128 v[240:243], v45 offset:7168
	global_load_lds_dwordx4 v[40:41], off
	v_lshl_add_u64 v[40:41], s[20:21], 0, v[36:37]
	s_mov_b32 m0, s11
	s_nop 0
	global_load_lds_dwordx4 v[40:41], off
	s_waitcnt vmcnt(8) lgkmcnt(0)
	s_barrier
	s_setprio 1
	v_mfma_f32_16x16x32_bf16 v[78:81], v[118:121], v[190:193], v[78:81]
	v_mfma_f32_16x16x32_bf16 v[82:85], v[126:129], v[190:193], v[82:85]
	v_mfma_f32_16x16x32_bf16 v[86:89], v[118:121], v[198:201], v[86:89]
	v_mfma_f32_16x16x32_bf16 v[90:93], v[126:129], v[198:201], v[90:93]
	v_mfma_f32_16x16x32_bf16 v[94:97], v[118:121], v[206:209], v[94:97]
	v_mfma_f32_16x16x32_bf16 v[98:101], v[126:129], v[206:209], v[98:101]
	v_mfma_f32_16x16x32_bf16 v[102:105], v[118:121], v[236:239], v[102:105]
	v_mfma_f32_16x16x32_bf16 v[106:109], v[126:129], v[236:239], v[106:109]
	v_mfma_f32_16x16x32_bf16 v[78:81], v[122:125], v[194:197], v[78:81]
	v_mfma_f32_16x16x32_bf16 v[82:85], v[130:133], v[194:197], v[82:85]
	v_mfma_f32_16x16x32_bf16 v[86:89], v[122:125], v[202:205], v[86:89]
	v_mfma_f32_16x16x32_bf16 v[90:93], v[130:133], v[202:205], v[90:93]
	v_mfma_f32_16x16x32_bf16 v[94:97], v[122:125], v[232:235], v[94:97]
	v_mfma_f32_16x16x32_bf16 v[98:101], v[130:133], v[232:235], v[98:101]
	v_mfma_f32_16x16x32_bf16 v[102:105], v[122:125], v[240:243], v[102:105]
	v_mfma_f32_16x16x32_bf16 v[106:109], v[130:133], v[240:243], v[106:109]
	v_mfma_f32_16x16x32_bf16 v[110:113], v[134:137], v[190:193], v[110:113]
	v_mfma_f32_16x16x32_bf16 v[46:49], v[182:185], v[190:193], v[46:49]
	v_mfma_f32_16x16x32_bf16 v[50:53], v[134:137], v[198:201], v[50:53]
	v_mfma_f32_16x16x32_bf16 v[54:57], v[182:185], v[198:201], v[54:57]
	v_mfma_f32_16x16x32_bf16 v[58:61], v[134:137], v[206:209], v[58:61]
	v_mfma_f32_16x16x32_bf16 v[62:65], v[182:185], v[206:209], v[62:65]
	v_mfma_f32_16x16x32_bf16 v[66:69], v[134:137], v[236:239], v[66:69]
	v_mfma_f32_16x16x32_bf16 v[70:73], v[182:185], v[236:239], v[70:73]
	v_mfma_f32_16x16x32_bf16 v[110:113], v[138:141], v[194:197], v[110:113]
	v_mfma_f32_16x16x32_bf16 v[46:49], v[186:189], v[194:197], v[46:49]
	v_mfma_f32_16x16x32_bf16 v[50:53], v[138:141], v[202:205], v[50:53]
	v_mfma_f32_16x16x32_bf16 v[54:57], v[186:189], v[202:205], v[54:57]
	v_mfma_f32_16x16x32_bf16 v[58:61], v[138:141], v[232:235], v[58:61]
	v_mfma_f32_16x16x32_bf16 v[62:65], v[186:189], v[232:235], v[62:65]
	v_mfma_f32_16x16x32_bf16 v[66:69], v[138:141], v[240:243], v[66:69]
	v_mfma_f32_16x16x32_bf16 v[70:73], v[186:189], v[240:243], v[70:73]
	s_setprio 0
	s_barrier
	s_mov_b32 m0, s47
	v_lshl_add_u64 v[40:41], s[24:25], 0, v[0:1]
	s_add_u32 s20, s24, 0x10000
	ds_read_b128 v[190:193], v45 offset:16384
	ds_read_b128 v[194:197], v45 offset:17408
	ds_read_b128 v[198:201], v45 offset:18432
	ds_read_b128 v[202:205], v45 offset:19456
	ds_read_b128 v[206:209], v45 offset:20480
	ds_read_b128 v[232:235], v45 offset:21504
	ds_read_b128 v[236:239], v45 offset:22528
	ds_read_b128 v[240:243], v45 offset:23552
	global_load_lds_dwordx4 v[40:41], off
	v_lshl_add_u64 v[210:211], s[24:25], 0, v[38:39]
	s_mov_b32 m0, s13
	s_addc_u32 s21, s25, 0
	global_load_lds_dwordx4 v[210:211], off
	v_lshl_add_u64 v[220:221], s[20:21], 0, v[0:1]
	s_mov_b32 m0, s45
	v_lshl_add_u64 v[222:223], s[26:27], 0, v[36:37]
	global_load_lds_dwordx4 v[220:221], off
	v_lshl_add_u64 v[220:221], s[20:21], 0, v[38:39]
	s_mov_b32 m0, s46
	s_nop 0
	global_load_lds_dwordx4 v[220:221], off
	v_lshl_add_u64 v[220:221], s[26:27], 0, v[34:35]
	s_mov_b32 m0, s15
	s_nop 0
	global_load_lds_dwordx4 v[220:221], off
	s_mov_b32 m0, s37
	s_nop 0
	global_load_lds_dwordx4 v[222:223], off
	s_waitcnt vmcnt(8) lgkmcnt(0)
	s_barrier
	s_setprio 1
	v_mfma_f32_16x16x32_bf16 v[142:145], v[118:121], v[190:193], v[142:145]
	v_mfma_f32_16x16x32_bf16 v[162:165], v[126:129], v[190:193], v[162:165]
	v_mfma_f32_16x16x32_bf16 v[166:169], v[118:121], v[198:201], v[166:169]
	v_mfma_f32_16x16x32_bf16 v[170:173], v[126:129], v[198:201], v[170:173]
	v_mfma_f32_16x16x32_bf16 v[174:177], v[118:121], v[206:209], v[174:177]
	v_mfma_f32_16x16x32_bf16 v[178:181], v[126:129], v[206:209], v[178:181]
	v_mfma_f32_16x16x32_bf16 v[2:5], v[118:121], v[236:239], v[2:5]
	v_mfma_f32_16x16x32_bf16 v[6:9], v[126:129], v[236:239], v[6:9]
	v_mfma_f32_16x16x32_bf16 v[142:145], v[122:125], v[194:197], v[142:145]
	v_mfma_f32_16x16x32_bf16 v[162:165], v[130:133], v[194:197], v[162:165]
	v_mfma_f32_16x16x32_bf16 v[166:169], v[122:125], v[202:205], v[166:169]
	v_mfma_f32_16x16x32_bf16 v[170:173], v[130:133], v[202:205], v[170:173]
	v_mfma_f32_16x16x32_bf16 v[174:177], v[122:125], v[232:235], v[174:177]
	v_mfma_f32_16x16x32_bf16 v[178:181], v[130:133], v[232:235], v[178:181]
	v_mfma_f32_16x16x32_bf16 v[2:5], v[122:125], v[240:243], v[2:5]
	v_mfma_f32_16x16x32_bf16 v[6:9], v[130:133], v[240:243], v[6:9]
	v_mfma_f32_16x16x32_bf16 v[14:17], v[182:185], v[190:193], v[14:17]
	v_mfma_f32_16x16x32_bf16 v[118:121], v[186:189], v[194:197], v[14:17]
	v_mfma_f32_16x16x32_bf16 v[14:17], v[134:137], v[198:201], v[26:29]
	v_mfma_f32_16x16x32_bf16 v[26:29], v[138:141], v[202:205], v[14:17]
	v_mfma_f32_16x16x32_bf16 v[14:17], v[182:185], v[198:201], v[30:33]
	v_mfma_f32_16x16x32_bf16 v[122:125], v[186:189], v[202:205], v[14:17]
	v_mfma_f32_16x16x32_bf16 v[14:17], v[134:137], v[206:209], v[74:77]
	v_mfma_f32_16x16x32_bf16 v[74:77], v[138:141], v[232:235], v[14:17]
	v_mfma_f32_16x16x32_bf16 v[14:17], v[182:185], v[206:209], v[114:117]
	v_mfma_f32_16x16x32_bf16 v[114:117], v[186:189], v[232:235], v[14:17]
	v_mfma_f32_16x16x32_bf16 v[14:17], v[134:137], v[236:239], v[18:21]
	v_mfma_f32_16x16x32_bf16 v[10:13], v[134:137], v[190:193], v[10:13]
	v_mfma_f32_16x16x32_bf16 v[126:129], v[138:141], v[240:243], v[14:17]
	v_mfma_f32_16x16x32_bf16 v[14:17], v[182:185], v[236:239], v[22:25]
	v_mfma_f32_16x16x32_bf16 v[10:13], v[138:141], v[194:197], v[10:13]
	v_mfma_f32_16x16x32_bf16 v[130:133], v[186:189], v[240:243], v[14:17]
	s_setprio 0
	s_barrier
	s_nop 3
	ds_read_b128 v[14:17], v231
	ds_read_b128 v[18:21], v231 offset:1024
	ds_read_b128 v[134:137], v231 offset:2048
	ds_read_b128 v[138:141], v231 offset:3072
	ds_read_b128 v[182:185], v246
	ds_read_b128 v[186:189], v246 offset:1024
	ds_read_b128 v[190:193], v246 offset:2048
	ds_read_b128 v[194:197], v246 offset:3072
	s_add_u32 s20, s26, 0x10000
	s_addc_u32 s21, s27, 0
	s_mov_b32 m0, s38
	v_lshl_add_u64 v[244:245], s[20:21], 0, v[34:35]
	ds_read_b128 v[22:25], v45 offset:32768
	ds_read_b128 v[30:33], v45 offset:33792
	ds_read_b128 v[198:201], v45 offset:34816
	ds_read_b128 v[202:205], v45 offset:35840
	ds_read_b128 v[206:209], v45 offset:36864
	ds_read_b128 v[232:235], v45 offset:37888
	ds_read_b128 v[236:239], v45 offset:38912
	ds_read_b128 v[240:243], v45 offset:39936
	global_load_lds_dwordx4 v[244:245], off
	v_lshl_add_u64 v[244:245], s[20:21], 0, v[36:37]
	s_mov_b32 m0, s39
	s_nop 0
	global_load_lds_dwordx4 v[244:245], off
	s_waitcnt vmcnt(8) lgkmcnt(0)
	s_barrier
	s_setprio 1
	v_mfma_f32_16x16x32_bf16 v[78:81], v[14:17], v[22:25], v[78:81]
	v_mfma_f32_16x16x32_bf16 v[82:85], v[134:137], v[22:25], v[82:85]
	v_mfma_f32_16x16x32_bf16 v[86:89], v[14:17], v[198:201], v[86:89]
	v_mfma_f32_16x16x32_bf16 v[90:93], v[134:137], v[198:201], v[90:93]
	v_mfma_f32_16x16x32_bf16 v[94:97], v[14:17], v[206:209], v[94:97]
	v_mfma_f32_16x16x32_bf16 v[98:101], v[134:137], v[206:209], v[98:101]
	v_mfma_f32_16x16x32_bf16 v[102:105], v[14:17], v[236:239], v[102:105]
	v_mfma_f32_16x16x32_bf16 v[106:109], v[134:137], v[236:239], v[106:109]
	v_mfma_f32_16x16x32_bf16 v[78:81], v[18:21], v[30:33], v[78:81]
	v_mfma_f32_16x16x32_bf16 v[82:85], v[138:141], v[30:33], v[82:85]
	v_mfma_f32_16x16x32_bf16 v[86:89], v[18:21], v[202:205], v[86:89]
	v_mfma_f32_16x16x32_bf16 v[90:93], v[138:141], v[202:205], v[90:93]
	v_mfma_f32_16x16x32_bf16 v[94:97], v[18:21], v[232:235], v[94:97]
	v_mfma_f32_16x16x32_bf16 v[98:101], v[138:141], v[232:235], v[98:101]
	v_mfma_f32_16x16x32_bf16 v[102:105], v[18:21], v[240:243], v[102:105]
	v_mfma_f32_16x16x32_bf16 v[106:109], v[138:141], v[240:243], v[106:109]
	v_mfma_f32_16x16x32_bf16 v[110:113], v[182:185], v[22:25], v[110:113]
	v_mfma_f32_16x16x32_bf16 v[22:25], v[190:193], v[22:25], v[46:49]
	v_mfma_f32_16x16x32_bf16 v[46:49], v[194:197], v[30:33], v[22:25]
	v_mfma_f32_16x16x32_bf16 v[22:25], v[182:185], v[198:201], v[50:53]
	v_mfma_f32_16x16x32_bf16 v[50:53], v[186:189], v[202:205], v[22:25]
	v_mfma_f32_16x16x32_bf16 v[22:25], v[190:193], v[198:201], v[54:57]
	v_mfma_f32_16x16x32_bf16 v[54:57], v[194:197], v[202:205], v[22:25]
	v_mfma_f32_16x16x32_bf16 v[22:25], v[182:185], v[206:209], v[58:61]
	v_mfma_f32_16x16x32_bf16 v[58:61], v[186:189], v[232:235], v[22:25]
	v_mfma_f32_16x16x32_bf16 v[22:25], v[190:193], v[206:209], v[62:65]
	v_mfma_f32_16x16x32_bf16 v[62:65], v[194:197], v[232:235], v[22:25]
	v_mfma_f32_16x16x32_bf16 v[22:25], v[182:185], v[236:239], v[66:69]
	v_mfma_f32_16x16x32_bf16 v[66:69], v[186:189], v[240:243], v[22:25]
	v_mfma_f32_16x16x32_bf16 v[22:25], v[190:193], v[236:239], v[70:73]
	v_mfma_f32_16x16x32_bf16 v[110:113], v[186:189], v[30:33], v[110:113]
	v_mfma_f32_16x16x32_bf16 v[70:73], v[194:197], v[240:243], v[22:25]
	s_setprio 0
	s_barrier
	s_mov_b32 m0, s54
	s_nop 2
	v_lshl_add_u64 v[22:23], v[40:41], 0, s[90:91]
	s_add_u32 s20, s24, 0x10080
	ds_read_b128 v[198:201], v45 offset:49152
	ds_read_b128 v[202:205], v45 offset:50176
	ds_read_b128 v[206:209], v45 offset:51200
	ds_read_b128 v[232:235], v45 offset:52224
	ds_read_b128 v[236:239], v45 offset:53248
	ds_read_b128 v[240:243], v45 offset:54272
	ds_read_b128 v[244:247], v45 offset:55296
	ds_read_b128 v[248:251], v45 offset:56320
	global_load_lds_dwordx4 v[22:23], off
	v_lshl_add_u64 v[22:23], v[210:211], 0, s[90:91]
	s_mov_b32 m0, s52
	s_addc_u32 s21, s25, 0
	global_load_lds_dwordx4 v[22:23], off
	v_lshl_add_u64 v[22:23], s[20:21], 0, v[0:1]
	s_mov_b32 m0, s22
	s_nop 0
	global_load_lds_dwordx4 v[22:23], off
	v_lshl_add_u64 v[22:23], s[20:21], 0, v[38:39]
	s_mov_b32 m0, s23
	s_nop 0
	global_load_lds_dwordx4 v[22:23], off
	v_lshl_add_u64 v[22:23], v[220:221], 0, s[90:91]
	s_mov_b32 m0, s40
	s_nop 0
	global_load_lds_dwordx4 v[22:23], off
	v_lshl_add_u64 v[22:23], v[222:223], 0, s[90:91]
	s_mov_b32 m0, s41
	s_nop 0
	global_load_lds_dwordx4 v[22:23], off
	s_waitcnt vmcnt(8) lgkmcnt(0)
	s_barrier
	s_setprio 1
	v_mfma_f32_16x16x32_bf16 v[22:25], v[14:17], v[198:201], v[142:145]
	v_mfma_f32_16x16x32_bf16 v[142:145], v[18:21], v[202:205], v[22:25]
	v_mfma_f32_16x16x32_bf16 v[22:25], v[134:137], v[198:201], v[162:165]
	v_mfma_f32_16x16x32_bf16 v[162:165], v[138:141], v[202:205], v[22:25]
	v_mfma_f32_16x16x32_bf16 v[22:25], v[14:17], v[206:209], v[166:169]
	v_mfma_f32_16x16x32_bf16 v[166:169], v[18:21], v[232:235], v[22:25]
	v_mfma_f32_16x16x32_bf16 v[22:25], v[134:137], v[206:209], v[170:173]
	v_mfma_f32_16x16x32_bf16 v[170:173], v[138:141], v[232:235], v[22:25]
	v_mfma_f32_16x16x32_bf16 v[22:25], v[14:17], v[236:239], v[174:177]
	v_mfma_f32_16x16x32_bf16 v[2:5], v[14:17], v[244:247], v[2:5]
	v_mfma_f32_16x16x32_bf16 v[30:33], v[18:21], v[240:243], v[22:25]
	v_mfma_f32_16x16x32_bf16 v[22:25], v[134:137], v[236:239], v[178:181]
	v_mfma_f32_16x16x32_bf16 v[14:17], v[18:21], v[248:251], v[2:5]
	v_mfma_f32_16x16x32_bf16 v[2:5], v[134:137], v[244:247], v[6:9]
	v_mfma_f32_16x16x32_bf16 v[22:25], v[138:141], v[240:243], v[22:25]
	v_mfma_f32_16x16x32_bf16 v[6:9], v[138:141], v[248:251], v[2:5]
	v_mfma_f32_16x16x32_bf16 v[2:5], v[182:185], v[198:201], v[10:13]
	v_mfma_f32_16x16x32_bf16 v[134:137], v[186:189], v[202:205], v[2:5]
	v_mfma_f32_16x16x32_bf16 v[2:5], v[190:193], v[198:201], v[118:121]
	v_mfma_f32_16x16x32_bf16 v[118:121], v[194:197], v[202:205], v[2:5]
	v_mfma_f32_16x16x32_bf16 v[2:5], v[182:185], v[206:209], v[26:29]
	v_mfma_f32_16x16x32_bf16 v[138:141], v[186:189], v[232:235], v[2:5]
	v_mfma_f32_16x16x32_bf16 v[2:5], v[190:193], v[206:209], v[122:125]
	v_mfma_f32_16x16x32_bf16 v[122:125], v[194:197], v[232:235], v[2:5]
	v_mfma_f32_16x16x32_bf16 v[2:5], v[182:185], v[236:239], v[74:77]
	v_mfma_f32_16x16x32_bf16 v[26:29], v[186:189], v[240:243], v[2:5]
	v_mfma_f32_16x16x32_bf16 v[2:5], v[190:193], v[236:239], v[114:117]
	v_mfma_f32_16x16x32_bf16 v[18:21], v[194:197], v[240:243], v[2:5]
	v_mfma_f32_16x16x32_bf16 v[2:5], v[182:185], v[244:247], v[126:129]
	v_mfma_f32_16x16x32_bf16 v[10:13], v[186:189], v[248:251], v[2:5]
	v_mfma_f32_16x16x32_bf16 v[2:5], v[190:193], v[244:247], v[130:133]
	v_mfma_f32_16x16x32_bf16 v[2:5], v[194:197], v[248:251], v[2:5]
	s_setprio 0
	s_barrier
	v_lshl_add_u32 v114, s14, 8, v42
	v_lshl_or_b32 v40, s44, 8, v44
	v_ashrrev_i32_e32 v41, 31, v40
	v_ashrrev_i32_e32 v115, 31, v114
	v_lshl_add_u64 v[116:117], v[40:41], 1, s[8:9]
	v_lshlrev_b64 v[40:41], 16, v[114:115]
	v_lshl_add_u64 v[40:41], v[116:117], 0, v[40:41]
	v_cvt_pk_bf16_f32 v74, v78, v79
	v_cvt_pk_bf16_f32 v75, v80, v81
	v_cvt_pk_bf16_f32 v76, v82, v83
	v_cvt_pk_bf16_f32 v77, v84, v85
	global_store_dwordx4 v[40:41], v[74:77], off
	s_mov_b64 s[20:21], 0x800000
	s_mov_b32 s11, 0x900000
	v_cvt_pk_bf16_f32 v74, v110, v111
	v_cvt_pk_bf16_f32 v75, v112, v113
	v_cvt_pk_bf16_f32 v76, v46, v47
	v_or_b32_e32 v46, 16, v114
	v_ashrrev_i32_e32 v47, 31, v46
	v_lshlrev_b64 v[46:47], 16, v[46:47]
	v_cvt_pk_bf16_f32 v77, v48, v49
	global_store_dwordx4 v[40:41], v[74:77], off offset:256
	s_add_i32 s43, s43, s28
	s_mov_b32 s44, s10
	v_lshl_add_u64 v[74:75], v[116:117], 0, v[46:47]
	v_cvt_pk_bf16_f32 v46, v86, v87
	v_cvt_pk_bf16_f32 v47, v88, v89
	v_cvt_pk_bf16_f32 v48, v90, v91
	v_cvt_pk_bf16_f32 v49, v92, v93
	global_store_dwordx4 v[74:75], v[46:49], off
	s_mov_b32 s14, s12
	s_mov_b64 s[22:23], s[18:19]
	v_cvt_pk_bf16_f32 v46, v50, v51
	v_cvt_pk_bf16_f32 v47, v52, v53
	v_cvt_pk_bf16_f32 v48, v54, v55
	v_cvt_pk_bf16_f32 v49, v56, v57
	global_store_dwordx4 v[74:75], v[46:49], off offset:256
	v_add_co_u32_e32 v52, vcc, s89, v40
	s_nop 0
	v_or_b32_e32 v46, 32, v114
	v_ashrrev_i32_e32 v47, 31, v46
	v_lshlrev_b64 v[46:47], 16, v[46:47]
	v_lshl_add_u64 v[50:51], v[116:117], 0, v[46:47]
	v_cvt_pk_bf16_f32 v46, v94, v95
	v_cvt_pk_bf16_f32 v47, v96, v97
	v_cvt_pk_bf16_f32 v48, v98, v99
	v_cvt_pk_bf16_f32 v49, v100, v101
	global_store_dwordx4 v[50:51], v[46:49], off
	v_addc_co_u32_e32 v53, vcc, 0, v41, vcc
	s_nop 0
	v_cvt_pk_bf16_f32 v46, v58, v59
	v_cvt_pk_bf16_f32 v47, v60, v61
	v_cvt_pk_bf16_f32 v48, v62, v63
	v_cvt_pk_bf16_f32 v49, v64, v65
	global_store_dwordx4 v[50:51], v[46:49], off offset:256
	s_nop 1
	v_or_b32_e32 v46, 48, v114
	v_ashrrev_i32_e32 v47, 31, v46
	v_lshlrev_b64 v[46:47], 16, v[46:47]
	v_lshl_add_u64 v[50:51], v[116:117], 0, v[46:47]
	v_cvt_pk_bf16_f32 v46, v102, v103
	v_cvt_pk_bf16_f32 v47, v104, v105
	v_cvt_pk_bf16_f32 v48, v106, v107
	v_cvt_pk_bf16_f32 v49, v108, v109
	global_store_dwordx4 v[50:51], v[46:49], off
	s_nop 1
	v_cvt_pk_bf16_f32 v46, v66, v67
	v_cvt_pk_bf16_f32 v47, v68, v69
	v_cvt_pk_bf16_f32 v48, v70, v71
	v_cvt_pk_bf16_f32 v49, v72, v73
	global_store_dwordx4 v[50:51], v[46:49], off offset:256
	v_lshl_add_u64 v[50:51], v[40:41], 0, s[20:21]
	s_mov_b64 s[20:21], 0x900000
	v_cvt_pk_bf16_f32 v46, v142, v143
	v_cvt_pk_bf16_f32 v47, v144, v145
	v_cvt_pk_bf16_f32 v48, v162, v163
	v_cvt_pk_bf16_f32 v49, v164, v165
	global_store_dwordx4 v[52:53], v[46:49], off
	v_add_co_u32_e32 v52, vcc, s11, v40
	s_nop 0
	v_cvt_pk_bf16_f32 v46, v134, v135
	v_cvt_pk_bf16_f32 v47, v136, v137
	v_cvt_pk_bf16_f32 v48, v118, v119
	v_cvt_pk_bf16_f32 v49, v120, v121
	global_store_dwordx4 v[50:51], v[46:49], off offset:256
	v_lshl_add_u64 v[50:51], v[40:41], 0, s[20:21]
	v_addc_co_u32_e32 v53, vcc, 0, v41, vcc
	v_cvt_pk_bf16_f32 v46, v166, v167
	v_cvt_pk_bf16_f32 v47, v168, v169
	v_cvt_pk_bf16_f32 v48, v170, v171
	v_cvt_pk_bf16_f32 v49, v172, v173
	s_mov_b32 s11, 0xa00000
	global_store_dwordx4 v[52:53], v[46:49], off
	s_mov_b64 s[20:21], 0xa00000
	s_nop 0
	v_cvt_pk_bf16_f32 v46, v138, v139
	v_cvt_pk_bf16_f32 v47, v140, v141
	v_cvt_pk_bf16_f32 v48, v122, v123
	v_cvt_pk_bf16_f32 v49, v124, v125
	global_store_dwordx4 v[50:51], v[46:49], off offset:256
	v_cvt_pk_bf16_f32 v30, v30, v31
	v_cvt_pk_bf16_f32 v31, v32, v33
	v_cvt_pk_bf16_f32 v32, v22, v23
	v_add_co_u32_e32 v22, vcc, s11, v40
	s_nop 0
	v_lshl_add_u64 v[46:47], v[40:41], 0, s[20:21]
	v_addc_co_u32_e32 v23, vcc, 0, v41, vcc
	s_mov_b32 s11, 0xb00000
	v_cvt_pk_bf16_f32 v33, v24, v25
	global_store_dwordx4 v[22:23], v[30:33], off
	v_cvt_pk_bf16_f32 v22, v26, v27
	v_cvt_pk_bf16_f32 v23, v28, v29
	v_cvt_pk_bf16_f32 v24, v18, v19
	v_cvt_pk_bf16_f32 v25, v20, v21
	global_store_dwordx4 v[46:47], v[22:25], off offset:256
	v_cvt_pk_bf16_f32 v14, v14, v15
	v_cvt_pk_bf16_f32 v15, v16, v17
	v_cvt_pk_bf16_f32 v16, v6, v7
	v_add_co_u32_e32 v6, vcc, s11, v40
	s_mov_b64 s[20:21], 0xb00000
	s_nop 0
	v_addc_co_u32_e32 v7, vcc, 0, v41, vcc
	v_lshl_add_u64 v[18:19], v[40:41], 0, s[20:21]
	s_andn2_b64 vcc, exec, s[4:5]
	s_mov_b64 s[20:21], s[16:17]
	v_cvt_pk_bf16_f32 v17, v8, v9
	global_store_dwordx4 v[6:7], v[14:17], off
	v_cvt_pk_bf16_f32 v6, v10, v11
	v_cvt_pk_bf16_f32 v7, v12, v13
	v_cvt_pk_bf16_f32 v8, v2, v3
	v_cvt_pk_bf16_f32 v9, v4, v5
	global_store_dwordx4 v[18:19], v[6:9], off offset:256
	s_cbranch_vccz .LBB0_592

.LBB0_1217:
	s_add_u32 s22, s20, 0x100
	s_addc_u32 s23, s21, 0
	s_add_i32 s55, 0, 0x10000
	s_cmp_eq_u32 s54, 12
	s_cselect_b32 s27, s13, s23
	s_cselect_b32 s26, s46, s22
	v_add_u32_e32 v140, s55, v143
	s_cselect_b32 s25, s11, s53
	s_cselect_b32 s24, s47, s52
	s_add_i32 s56, 0, 0x14000
	ds_read_b128 v[136:139], v140
	ds_read_b128 v[162:165], v140 offset:1024
	ds_read_b128 v[166:169], v140 offset:2048
	ds_read_b128 v[170:173], v140 offset:3072
	v_add_u32_e32 v140, s56, v143
	ds_read_b128 v[174:177], v140
	ds_read_b128 v[178:181], v140 offset:1024
	ds_read_b128 v[182:185], v140 offset:2048
	ds_read_b128 v[186:189], v140 offset:3072
	v_lshl_add_u64 v[140:141], s[20:21], 0, v[132:133]
	s_add_i32 m0, s38, 0xc000
	ds_read_b128 v[190:193], v145
	ds_read_b128 v[194:197], v145 offset:1024
	ds_read_b128 v[198:201], v145 offset:2048
	ds_read_b128 v[202:205], v145 offset:3072
	ds_read_b128 v[206:209], v145 offset:4096
	ds_read_b128 v[220:223], v145 offset:5120
	ds_read_b128 v[232:235], v145 offset:6144
	ds_read_b128 v[236:239], v145 offset:7168
	global_load_lds_dwordx4 v[140:141], off
	v_lshl_add_u64 v[140:141], s[20:21], 0, v[134:135]
	s_add_i32 m0, s38, 0xe000
	s_nop 0
	global_load_lds_dwordx4 v[140:141], off
	s_waitcnt vmcnt(8) lgkmcnt(0)
	s_barrier
	s_setprio 1
	v_mfma_f32_16x16x32_bf16 v[126:129], v[136:139], v[190:193], v[126:129]
	v_mfma_f32_16x16x32_bf16 v[122:125], v[166:169], v[190:193], v[122:125]
	v_mfma_f32_16x16x32_bf16 v[110:113], v[136:139], v[198:201], v[110:113]
	v_mfma_f32_16x16x32_bf16 v[106:109], v[166:169], v[198:201], v[106:109]
	v_mfma_f32_16x16x32_bf16 v[94:97], v[136:139], v[206:209], v[94:97]
	v_mfma_f32_16x16x32_bf16 v[90:93], v[166:169], v[206:209], v[90:93]
	v_mfma_f32_16x16x32_bf16 v[78:81], v[136:139], v[232:235], v[78:81]
	v_mfma_f32_16x16x32_bf16 v[74:77], v[166:169], v[232:235], v[74:77]
	v_mfma_f32_16x16x32_bf16 v[126:129], v[162:165], v[194:197], v[126:129]
	v_mfma_f32_16x16x32_bf16 v[122:125], v[170:173], v[194:197], v[122:125]
	v_mfma_f32_16x16x32_bf16 v[110:113], v[162:165], v[202:205], v[110:113]
	v_mfma_f32_16x16x32_bf16 v[106:109], v[170:173], v[202:205], v[106:109]
	v_mfma_f32_16x16x32_bf16 v[94:97], v[162:165], v[220:223], v[94:97]
	v_mfma_f32_16x16x32_bf16 v[90:93], v[170:173], v[220:223], v[90:93]
	v_mfma_f32_16x16x32_bf16 v[78:81], v[162:165], v[236:239], v[78:81]
	v_mfma_f32_16x16x32_bf16 v[74:77], v[170:173], v[236:239], v[74:77]
	v_mfma_f32_16x16x32_bf16 v[118:121], v[174:177], v[190:193], v[118:121]
	v_mfma_f32_16x16x32_bf16 v[114:117], v[182:185], v[190:193], v[114:117]
	v_mfma_f32_16x16x32_bf16 v[102:105], v[174:177], v[198:201], v[102:105]
	v_mfma_f32_16x16x32_bf16 v[98:101], v[182:185], v[198:201], v[98:101]
	v_mfma_f32_16x16x32_bf16 v[86:89], v[174:177], v[206:209], v[86:89]
	v_mfma_f32_16x16x32_bf16 v[82:85], v[182:185], v[206:209], v[82:85]
	v_mfma_f32_16x16x32_bf16 v[70:73], v[174:177], v[232:235], v[70:73]
	v_mfma_f32_16x16x32_bf16 v[66:69], v[182:185], v[232:235], v[66:69]
	v_mfma_f32_16x16x32_bf16 v[118:121], v[178:181], v[194:197], v[118:121]
	v_mfma_f32_16x16x32_bf16 v[114:117], v[186:189], v[194:197], v[114:117]
	v_mfma_f32_16x16x32_bf16 v[102:105], v[178:181], v[202:205], v[102:105]
	v_mfma_f32_16x16x32_bf16 v[98:101], v[186:189], v[202:205], v[98:101]
	v_mfma_f32_16x16x32_bf16 v[86:89], v[178:181], v[220:223], v[86:89]
	v_mfma_f32_16x16x32_bf16 v[82:85], v[186:189], v[220:223], v[82:85]
	v_mfma_f32_16x16x32_bf16 v[70:73], v[178:181], v[236:239], v[70:73]
	v_mfma_f32_16x16x32_bf16 v[66:69], v[186:189], v[236:239], v[66:69]
	s_setprio 0
	s_barrier
	s_add_i32 s20, s55, s37
	v_lshl_add_u64 v[140:141], s[24:25], 0, v[0:1]
	s_mov_b32 m0, s20
	ds_read_b128 v[190:193], v145 offset:16384
	ds_read_b128 v[194:197], v145 offset:17408
	ds_read_b128 v[198:201], v145 offset:18432
	ds_read_b128 v[202:205], v145 offset:19456
	ds_read_b128 v[206:209], v145 offset:20480
	ds_read_b128 v[220:223], v145 offset:21504
	ds_read_b128 v[232:235], v145 offset:22528
	ds_read_b128 v[236:239], v145 offset:23552
	global_load_lds_dwordx4 v[140:141], off
	s_add_i32 m0, s20, 0x2000
	s_add_u32 s20, s24, 0x40000
	v_lshl_add_u64 v[210:211], s[24:25], 0, v[130:131]
	s_addc_u32 s21, s25, 0
	s_add_i32 s55, s56, s37
	global_load_lds_dwordx4 v[210:211], off
	v_lshl_add_u64 v[240:241], s[20:21], 0, v[0:1]
	s_mov_b32 m0, s55
	v_lshl_add_u64 v[242:243], s[26:27], 0, v[130:131]
	global_load_lds_dwordx4 v[240:241], off
	v_lshl_add_u64 v[240:241], s[20:21], 0, v[130:131]
	s_add_i32 m0, s55, 0x2000
	s_nop 0
	global_load_lds_dwordx4 v[240:241], off
	v_lshl_add_u64 v[240:241], s[26:27], 0, v[0:1]
	s_mov_b32 m0, s38
	s_nop 0
	global_load_lds_dwordx4 v[240:241], off
	s_mov_b32 m0, s39
	s_nop 0
	global_load_lds_dwordx4 v[242:243], off
	s_waitcnt vmcnt(8) lgkmcnt(0)
	s_barrier
	s_setprio 1
	v_mfma_f32_16x16x32_bf16 v[62:65], v[136:139], v[190:193], v[62:65]
	v_mfma_f32_16x16x32_bf16 v[58:61], v[166:169], v[190:193], v[58:61]
	v_mfma_f32_16x16x32_bf16 v[46:49], v[136:139], v[198:201], v[46:49]
	v_mfma_f32_16x16x32_bf16 v[42:45], v[166:169], v[198:201], v[42:45]
	v_mfma_f32_16x16x32_bf16 v[30:33], v[136:139], v[206:209], v[30:33]
	v_mfma_f32_16x16x32_bf16 v[26:29], v[166:169], v[206:209], v[26:29]
	v_mfma_f32_16x16x32_bf16 v[14:17], v[136:139], v[232:235], v[14:17]
	v_mfma_f32_16x16x32_bf16 v[10:13], v[166:169], v[232:235], v[10:13]
	v_mfma_f32_16x16x32_bf16 v[62:65], v[162:165], v[194:197], v[62:65]
	v_mfma_f32_16x16x32_bf16 v[58:61], v[170:173], v[194:197], v[58:61]
	v_mfma_f32_16x16x32_bf16 v[46:49], v[162:165], v[202:205], v[46:49]
	v_mfma_f32_16x16x32_bf16 v[42:45], v[170:173], v[202:205], v[42:45]
	v_mfma_f32_16x16x32_bf16 v[30:33], v[162:165], v[220:223], v[30:33]
	v_mfma_f32_16x16x32_bf16 v[26:29], v[170:173], v[220:223], v[26:29]
	v_mfma_f32_16x16x32_bf16 v[14:17], v[162:165], v[236:239], v[14:17]
	v_mfma_f32_16x16x32_bf16 v[10:13], v[170:173], v[236:239], v[10:13]
	v_mfma_f32_16x16x32_bf16 v[54:57], v[174:177], v[190:193], v[54:57]
	v_mfma_f32_16x16x32_bf16 v[50:53], v[182:185], v[190:193], v[50:53]
	v_mfma_f32_16x16x32_bf16 v[38:41], v[174:177], v[198:201], v[38:41]
	v_mfma_f32_16x16x32_bf16 v[34:37], v[182:185], v[198:201], v[34:37]
	v_mfma_f32_16x16x32_bf16 v[22:25], v[174:177], v[206:209], v[22:25]
	v_mfma_f32_16x16x32_bf16 v[18:21], v[182:185], v[206:209], v[18:21]
	v_mfma_f32_16x16x32_bf16 v[6:9], v[174:177], v[232:235], v[6:9]
	v_mfma_f32_16x16x32_bf16 v[2:5], v[182:185], v[232:235], v[2:5]
	v_mfma_f32_16x16x32_bf16 v[54:57], v[178:181], v[194:197], v[54:57]
	v_mfma_f32_16x16x32_bf16 v[50:53], v[186:189], v[194:197], v[50:53]
	v_mfma_f32_16x16x32_bf16 v[38:41], v[178:181], v[202:205], v[38:41]
	v_mfma_f32_16x16x32_bf16 v[34:37], v[186:189], v[202:205], v[34:37]
	v_mfma_f32_16x16x32_bf16 v[22:25], v[178:181], v[220:223], v[22:25]
	v_mfma_f32_16x16x32_bf16 v[18:21], v[186:189], v[220:223], v[18:21]
	v_mfma_f32_16x16x32_bf16 v[6:9], v[178:181], v[236:239], v[6:9]
	v_mfma_f32_16x16x32_bf16 v[2:5], v[186:189], v[236:239], v[2:5]
	s_setprio 0
	s_barrier
	s_add_i32 s55, 0, 0x18000
	v_add_u32_e32 v146, s55, v143
	s_add_i32 s56, 0, 0x1c000
	ds_read_b128 v[136:139], v146
	ds_read_b128 v[162:165], v146 offset:1024
	ds_read_b128 v[166:169], v146 offset:2048
	ds_read_b128 v[170:173], v146 offset:3072
	v_add_u32_e32 v146, s56, v143
	ds_read_b128 v[174:177], v146
	ds_read_b128 v[178:181], v146 offset:1024
	ds_read_b128 v[182:185], v146 offset:2048
	ds_read_b128 v[186:189], v146 offset:3072
	s_add_u32 s20, s26, 0x40000
	s_addc_u32 s21, s27, 0
	s_mov_b32 m0, s40
	v_lshl_add_u64 v[244:245], s[20:21], 0, v[0:1]
	ds_read_b128 v[190:193], v145 offset:32768
	ds_read_b128 v[194:197], v145 offset:33792
	ds_read_b128 v[198:201], v145 offset:34816
	ds_read_b128 v[202:205], v145 offset:35840
	ds_read_b128 v[206:209], v145 offset:36864
	ds_read_b128 v[220:223], v145 offset:37888
	ds_read_b128 v[232:235], v145 offset:38912
	ds_read_b128 v[236:239], v145 offset:39936
	global_load_lds_dwordx4 v[244:245], off
	v_lshl_add_u64 v[244:245], s[20:21], 0, v[130:131]
	s_mov_b32 m0, s41
	s_nop 0
	global_load_lds_dwordx4 v[244:245], off
	s_waitcnt vmcnt(8) lgkmcnt(0)
	s_barrier
	s_setprio 1
	v_mfma_f32_16x16x32_bf16 v[126:129], v[136:139], v[190:193], v[126:129]
	v_mfma_f32_16x16x32_bf16 v[122:125], v[166:169], v[190:193], v[122:125]
	v_mfma_f32_16x16x32_bf16 v[110:113], v[136:139], v[198:201], v[110:113]
	v_mfma_f32_16x16x32_bf16 v[106:109], v[166:169], v[198:201], v[106:109]
	v_mfma_f32_16x16x32_bf16 v[94:97], v[136:139], v[206:209], v[94:97]
	v_mfma_f32_16x16x32_bf16 v[90:93], v[166:169], v[206:209], v[90:93]
	v_mfma_f32_16x16x32_bf16 v[78:81], v[136:139], v[232:235], v[78:81]
	v_mfma_f32_16x16x32_bf16 v[74:77], v[166:169], v[232:235], v[74:77]
	v_mfma_f32_16x16x32_bf16 v[126:129], v[162:165], v[194:197], v[126:129]
	v_mfma_f32_16x16x32_bf16 v[122:125], v[170:173], v[194:197], v[122:125]
	v_mfma_f32_16x16x32_bf16 v[110:113], v[162:165], v[202:205], v[110:113]
	v_mfma_f32_16x16x32_bf16 v[106:109], v[170:173], v[202:205], v[106:109]
	v_mfma_f32_16x16x32_bf16 v[94:97], v[162:165], v[220:223], v[94:97]
	v_mfma_f32_16x16x32_bf16 v[90:93], v[170:173], v[220:223], v[90:93]
	v_mfma_f32_16x16x32_bf16 v[78:81], v[162:165], v[236:239], v[78:81]
	v_mfma_f32_16x16x32_bf16 v[74:77], v[170:173], v[236:239], v[74:77]
	v_mfma_f32_16x16x32_bf16 v[118:121], v[174:177], v[190:193], v[118:121]
	v_mfma_f32_16x16x32_bf16 v[114:117], v[182:185], v[190:193], v[114:117]
	v_mfma_f32_16x16x32_bf16 v[102:105], v[174:177], v[198:201], v[102:105]
	v_mfma_f32_16x16x32_bf16 v[98:101], v[182:185], v[198:201], v[98:101]
	v_mfma_f32_16x16x32_bf16 v[86:89], v[174:177], v[206:209], v[86:89]
	v_mfma_f32_16x16x32_bf16 v[82:85], v[182:185], v[206:209], v[82:85]
	v_mfma_f32_16x16x32_bf16 v[70:73], v[174:177], v[232:235], v[70:73]
	v_mfma_f32_16x16x32_bf16 v[66:69], v[182:185], v[232:235], v[66:69]
	v_mfma_f32_16x16x32_bf16 v[118:121], v[178:181], v[194:197], v[118:121]
	v_mfma_f32_16x16x32_bf16 v[114:117], v[186:189], v[194:197], v[114:117]
	v_mfma_f32_16x16x32_bf16 v[102:105], v[178:181], v[202:205], v[102:105]
	v_mfma_f32_16x16x32_bf16 v[98:101], v[186:189], v[202:205], v[98:101]
	v_mfma_f32_16x16x32_bf16 v[86:89], v[178:181], v[220:223], v[86:89]
	v_mfma_f32_16x16x32_bf16 v[82:85], v[186:189], v[220:223], v[82:85]
	v_mfma_f32_16x16x32_bf16 v[70:73], v[178:181], v[236:239], v[70:73]
	v_mfma_f32_16x16x32_bf16 v[66:69], v[186:189], v[236:239], v[66:69]
	s_setprio 0
	s_barrier
	s_add_i32 s20, s55, s37
	v_lshl_add_u64 v[140:141], v[140:141], 0, s[90:91]
	s_mov_b32 m0, s20
	ds_read_b128 v[190:193], v145 offset:49152
	ds_read_b128 v[194:197], v145 offset:50176
	ds_read_b128 v[198:201], v145 offset:51200
	ds_read_b128 v[202:205], v145 offset:52224
	ds_read_b128 v[206:209], v145 offset:53248
	ds_read_b128 v[220:223], v145 offset:54272
	ds_read_b128 v[232:235], v145 offset:55296
	ds_read_b128 v[236:239], v145 offset:56320
	global_load_lds_dwordx4 v[140:141], off
	s_add_i32 m0, s20, 0x2000
	s_add_u32 s20, s24, 0x40080
	v_lshl_add_u64 v[140:141], v[210:211], 0, s[90:91]
	s_addc_u32 s21, s25, 0
	s_add_i32 s24, s56, s37
	global_load_lds_dwordx4 v[140:141], off
	v_lshl_add_u64 v[140:141], s[20:21], 0, v[0:1]
	s_mov_b32 m0, s24
	s_nop 0
	global_load_lds_dwordx4 v[140:141], off
	v_lshl_add_u64 v[140:141], s[20:21], 0, v[130:131]
	s_add_i32 m0, s24, 0x2000
	s_nop 0
	global_load_lds_dwordx4 v[140:141], off
	v_lshl_add_u64 v[140:141], v[240:241], 0, s[90:91]
	s_mov_b32 m0, s42
	s_nop 0
	global_load_lds_dwordx4 v[140:141], off
	v_lshl_add_u64 v[140:141], v[242:243], 0, s[90:91]
	s_mov_b32 m0, s43
	s_nop 0
	global_load_lds_dwordx4 v[140:141], off
	s_waitcnt vmcnt(8) lgkmcnt(0)
	s_barrier
	s_setprio 1
	v_mfma_f32_16x16x32_bf16 v[62:65], v[136:139], v[190:193], v[62:65]
	v_mfma_f32_16x16x32_bf16 v[58:61], v[166:169], v[190:193], v[58:61]
	v_mfma_f32_16x16x32_bf16 v[46:49], v[136:139], v[198:201], v[46:49]
	v_mfma_f32_16x16x32_bf16 v[42:45], v[166:169], v[198:201], v[42:45]
	v_mfma_f32_16x16x32_bf16 v[30:33], v[136:139], v[206:209], v[30:33]
	v_mfma_f32_16x16x32_bf16 v[26:29], v[166:169], v[206:209], v[26:29]
	v_mfma_f32_16x16x32_bf16 v[14:17], v[136:139], v[232:235], v[14:17]
	v_mfma_f32_16x16x32_bf16 v[10:13], v[166:169], v[232:235], v[10:13]
	v_mfma_f32_16x16x32_bf16 v[62:65], v[162:165], v[194:197], v[62:65]
	v_mfma_f32_16x16x32_bf16 v[58:61], v[170:173], v[194:197], v[58:61]
	v_mfma_f32_16x16x32_bf16 v[46:49], v[162:165], v[202:205], v[46:49]
	v_mfma_f32_16x16x32_bf16 v[42:45], v[170:173], v[202:205], v[42:45]
	v_mfma_f32_16x16x32_bf16 v[30:33], v[162:165], v[220:223], v[30:33]
	v_mfma_f32_16x16x32_bf16 v[26:29], v[170:173], v[220:223], v[26:29]
	v_mfma_f32_16x16x32_bf16 v[14:17], v[162:165], v[236:239], v[14:17]
	v_mfma_f32_16x16x32_bf16 v[10:13], v[170:173], v[236:239], v[10:13]
	v_mfma_f32_16x16x32_bf16 v[54:57], v[174:177], v[190:193], v[54:57]
	v_mfma_f32_16x16x32_bf16 v[50:53], v[182:185], v[190:193], v[50:53]
	v_mfma_f32_16x16x32_bf16 v[38:41], v[174:177], v[198:201], v[38:41]
	v_mfma_f32_16x16x32_bf16 v[34:37], v[182:185], v[198:201], v[34:37]
	v_mfma_f32_16x16x32_bf16 v[22:25], v[174:177], v[206:209], v[22:25]
	v_mfma_f32_16x16x32_bf16 v[18:21], v[182:185], v[206:209], v[18:21]
	v_mfma_f32_16x16x32_bf16 v[6:9], v[174:177], v[232:235], v[6:9]
	v_mfma_f32_16x16x32_bf16 v[2:5], v[182:185], v[232:235], v[2:5]
	v_mfma_f32_16x16x32_bf16 v[54:57], v[178:181], v[194:197], v[54:57]
	v_mfma_f32_16x16x32_bf16 v[50:53], v[186:189], v[194:197], v[50:53]
	v_mfma_f32_16x16x32_bf16 v[38:41], v[178:181], v[202:205], v[38:41]
	v_mfma_f32_16x16x32_bf16 v[34:37], v[186:189], v[202:205], v[34:37]
	v_mfma_f32_16x16x32_bf16 v[22:25], v[178:181], v[220:223], v[22:25]
	v_mfma_f32_16x16x32_bf16 v[18:21], v[186:189], v[220:223], v[18:21]
	v_mfma_f32_16x16x32_bf16 v[6:9], v[178:181], v[236:239], v[6:9]
	v_mfma_f32_16x16x32_bf16 v[2:5], v[186:189], v[236:239], v[2:5]
	s_setprio 0
	s_barrier
	s_add_i32 s54, s54, 2
	s_add_u32 s52, s52, 0x100
	s_addc_u32 s53, s53, 0
	s_cmp_gt_u32 s54, 13
	s_mov_b64 s[20:21], s[22:23]
	s_cbranch_scc0 .LBB0_1217
	s_and_b64 vcc, exec, s[8:9]
	s_cbranch_vccz .LBB0_1220
	s_barrier
